# v057 + CA-q/cross-attention same-workgroup fusion + static s_setprio 1 for waves 0-3 in the sparse-attention phase + LayerNorm gamma/beta copies removed
# baseline (speedup 1.0000x reference)
; template <int EPI>
; DI void gemm_unit(const GemmP& g, int pm, int pn) {
;     ...
; #pragma unroll
;     for (int ai = 0; ai < 2; ++ai)
; #pragma unroll
;       for (int m = 0; m < 4; ++m) {
;         const int rl = ai * 128 + wr * 64 + m * 16 + fr;
;         const float mean = mr[rl * 2], rs = mr[rl * 2 + 1];
;         const int row = row0 + ai * 128 + m * 16;
; #pragma unroll
;         for (int bj = 0; bj < 2; ++bj)
; #pragma unroll
;           for (int n = 0; n < 2; ++n) {
;             const int col = colb + bj * 128 + n * 16;
;             const f32x4 gg = *(const f32x4*)(g.ln_g + col), bb = *(const f32x4*)(g.ln_b + col);
;             const f32x4 o = (acc[ai][bj][m][n] - mean) * rs * gg + bb;
;             const size_t idx = (size_t)row * 2048 + col;
;             if (g.outf) *(f32x4*)(g.outf + idx) = o;
;             uint2 ob; ob.x = pk2(o[0], o[1]); ob.y = pk2(o[2], o[3]);
;             *(uint2*)(g.outb + idx) = ob;
;           }
.LBB0_81:
	s_or_b64 exec, exec, s[6:7]
	v_lshlrev_b64 v[186:187], 2, v[132:133]
	v_lshl_add_u64 v[130:131], s[52:53], 0, v[186:187]
	v_lshl_add_u64 v[186:187], s[10:11], 0, v[186:187]
	global_load_dwordx4 v[224:227], v[130:131], off
	global_load_dwordx4 v[228:231], v[130:131], off offset:64
	global_load_dwordx4 v[232:235], v[130:131], off offset:512
	global_load_dwordx4 v[236:239], v[130:131], off offset:576
	global_load_dwordx4 v[240:243], v[186:187], off
	global_load_dwordx4 v[244:247], v[186:187], off offset:64
	global_load_dwordx4 v[248:251], v[186:187], off offset:512
	global_load_dwordx4 v[194:197], v[186:187], off offset:576
	s_waitcnt lgkmcnt(0)
	s_barrier
	s_waitcnt vmcnt(0)
	v_lshlrev_b32_e32 v0, 3, v0
	v_add_u32_e32 v0, 0, v0
	ds_read_b64 v[188:189], v0 offset:8192
	v_cndmask_b32_e64 v133, 0, 1, s[20:21]
	v_cmp_ne_u32_e64 s[6:7], 1, v133
	s_andn2_b64 vcc, exec, s[20:21]
	s_waitcnt lgkmcnt(0)
	v_sub_f32_e32 v129, v129, v188
	v_sub_f32_e32 v128, v128, v188
	v_sub_f32_e32 v127, v127, v188
	v_sub_f32_e32 v126, v126, v188
	v_pk_mul_f32 v[126:127], v[188:189], v[126:127] op_sel:[1,0]
	v_pk_mul_f32 v[128:129], v[188:189], v[128:129] op_sel:[1,0]
	v_pk_fma_f32 v[2:3], v[224:225], v[126:127], v[240:241]
	v_pk_fma_f32 v[4:5], v[226:227], v[128:129], v[242:243]
	v_lshl_add_u64 v[126:127], v[138:139], 2, s[88:89]
	s_cbranch_vccnz .LBB0_83
	global_store_dwordx4 v[126:127], v[2:5], off
.LBB0_83:
	s_nop 1
	v_cvt_pk_bf16_f32 v2, v2, v3
	v_cvt_pk_bf16_f32 v3, v4, v5
	global_store_dwordx2 v[136:137], v[2:3], off
	s_nop 0
	v_mov_b32_e32 v128, v189
	v_mov_b32_e32 v129, v189
	v_sub_f32_e32 v123, v123, v188
	v_sub_f32_e32 v122, v122, v188
	v_sub_f32_e32 v191, v125, v188
	v_sub_f32_e32 v190, v124, v188
	v_mov_b32_e32 v124, v189
	v_mov_b32_e32 v125, v189
	v_pk_mul_f32 v[190:191], v[124:125], v[190:191]
	v_pk_mul_f32 v[122:123], v[128:129], v[122:123]
	s_and_b64 vcc, exec, s[6:7]
	v_pk_fma_f32 v[2:3], v[122:123], v[228:229], v[244:245]
	v_pk_fma_f32 v[4:5], v[190:191], v[230:231], v[246:247]
	s_cbranch_vccnz .LBB0_85
	global_store_dwordx4 v[126:127], v[2:5], off offset:64
.LBB0_85:
	v_or_b32_e32 v122, 16, v132
	v_ashrrev_i32_e32 v123, 31, v122
	v_lshl_add_u64 v[136:137], v[134:135], 0, v[122:123]
	v_cvt_pk_bf16_f32 v2, v2, v3
	v_cvt_pk_bf16_f32 v3, v4, v5
	v_lshl_add_u64 v[4:5], v[136:137], 1, s[66:67]
	global_store_dwordx2 v[4:5], v[2:3], off
	s_nop 0
	v_sub_f32_e32 v119, v119, v188
	v_sub_f32_e32 v118, v118, v188
	v_sub_f32_e32 v121, v121, v188
	v_sub_f32_e32 v120, v120, v188
	v_pk_mul_f32 v[120:121], v[124:125], v[120:121]
	v_pk_mul_f32 v[118:119], v[128:129], v[118:119]
	s_and_b64 vcc, exec, s[6:7]
	v_pk_fma_f32 v[2:3], v[118:119], v[232:233], v[248:249]
	v_pk_fma_f32 v[4:5], v[120:121], v[234:235], v[250:251]
	s_cbranch_vccnz .LBB0_87
	global_store_dwordx4 v[126:127], v[2:5], off offset:512
.LBB0_87:
	v_or_b32_e32 v118, 0x80, v132
	v_ashrrev_i32_e32 v119, 31, v118
	v_lshl_add_u64 v[120:121], v[134:135], 0, v[118:119]
	v_cvt_pk_bf16_f32 v2, v2, v3
	v_cvt_pk_bf16_f32 v3, v4, v5
	v_lshl_add_u64 v[4:5], v[120:121], 1, s[66:67]
	global_store_dwordx2 v[4:5], v[2:3], off
	s_nop 0
	v_sub_f32_e32 v115, v115, v188
	v_sub_f32_e32 v114, v114, v188
	v_sub_f32_e32 v117, v117, v188
	v_sub_f32_e32 v116, v116, v188
	v_mov_b32_e32 v188, v189
	v_pk_mul_f32 v[116:117], v[188:189], v[116:117]
	v_pk_mul_f32 v[114:115], v[128:129], v[114:115]
	s_and_b64 vcc, exec, s[6:7]
	v_pk_fma_f32 v[2:3], v[114:115], v[236:237], v[194:195]
	v_pk_fma_f32 v[4:5], v[116:117], v[238:239], v[196:197]
	s_cbranch_vccnz .LBB0_89
	global_store_dwordx4 v[126:127], v[2:5], off offset:576
.LBB0_89:
	v_or_b32_e32 v114, 0x90, v132
	v_ashrrev_i32_e32 v115, 31, v114
	v_lshl_add_u64 v[116:117], v[134:135], 0, v[114:115]
	v_cvt_pk_bf16_f32 v2, v2, v3
	v_cvt_pk_bf16_f32 v3, v4, v5
	v_lshl_add_u64 v[4:5], v[116:117], 1, s[66:67]
	global_store_dwordx2 v[4:5], v[2:3], off
	s_nop 0
	ds_read_b64 v[116:117], v0 offset:8320
	s_and_b64 vcc, exec, s[6:7]
	s_waitcnt lgkmcnt(0)
	v_sub_f32_e32 v111, v111, v116
	v_sub_f32_e32 v110, v110, v116
	v_sub_f32_e32 v113, v113, v116
	v_sub_f32_e32 v112, v112, v116
	v_pk_mul_f32 v[112:113], v[116:117], v[112:113] op_sel:[1,0]
	v_pk_mul_f32 v[110:111], v[116:117], v[110:111] op_sel:[1,0]
	v_pk_fma_f32 v[4:5], v[226:227], v[112:113], v[242:243]
	v_pk_fma_f32 v[2:3], v[224:225], v[110:111], v[240:241]
	v_lshl_add_u64 v[110:111], v[144:145], 2, s[88:89]
	s_cbranch_vccnz .LBB0_91
	global_store_dwordx4 v[110:111], v[2:5], off
.LBB0_91:
	s_nop 1
	v_cvt_pk_bf16_f32 v2, v2, v3
	v_cvt_pk_bf16_f32 v3, v4, v5
	global_store_dwordx2 v[142:143], v[2:3], off
	s_nop 0
	v_mov_b32_e32 v112, v117
	v_mov_b32_e32 v113, v117
	v_sub_f32_e32 v121, v107, v116
	v_sub_f32_e32 v120, v106, v116
	v_sub_f32_e32 v109, v109, v116
	v_sub_f32_e32 v108, v108, v116
	v_mov_b32_e32 v106, v117
	v_mov_b32_e32 v107, v117
	v_pk_mul_f32 v[108:109], v[106:107], v[108:109]
	v_pk_mul_f32 v[120:121], v[112:113], v[120:121]
	s_and_b64 vcc, exec, s[6:7]
	v_pk_fma_f32 v[2:3], v[120:121], v[228:229], v[244:245]
	v_pk_fma_f32 v[4:5], v[108:109], v[230:231], v[246:247]
	s_cbranch_vccnz .LBB0_93
	global_store_dwordx4 v[110:111], v[2:5], off offset:64
.LBB0_93:
	v_lshl_add_u64 v[108:109], v[140:141], 0, v[122:123]
	s_nop 0
	v_cvt_pk_bf16_f32 v2, v2, v3
	v_cvt_pk_bf16_f32 v3, v4, v5
	v_lshl_add_u64 v[4:5], v[108:109], 1, s[66:67]
	global_store_dwordx2 v[4:5], v[2:3], off
	s_nop 0
	v_sub_f32_e32 v103, v103, v116
	v_sub_f32_e32 v102, v102, v116
	v_sub_f32_e32 v105, v105, v116
	v_sub_f32_e32 v104, v104, v116
	v_pk_mul_f32 v[104:105], v[106:107], v[104:105]
	v_pk_mul_f32 v[102:103], v[112:113], v[102:103]
	s_and_b64 vcc, exec, s[6:7]
	v_pk_fma_f32 v[2:3], v[102:103], v[232:233], v[248:249]
	v_pk_fma_f32 v[4:5], v[104:105], v[234:235], v[250:251]
	s_cbranch_vccnz .LBB0_95
	global_store_dwordx4 v[110:111], v[2:5], off offset:512
; template <int EPI>
; DI void gemm_unit(const GemmP& g, int pm, int pn) {
;     ...
; #pragma unroll
;     for (int ai = 0; ai < 2; ++ai)
; #pragma unroll
;       for (int m = 0; m < 4; ++m) {
;         const int rl = ai * 128 + wr * 64 + m * 16 + fr;
;         const float mean = mr[rl * 2], rs = mr[rl * 2 + 1];
;         const int row = row0 + ai * 128 + m * 16;
; #pragma unroll
;         for (int bj = 0; bj < 2; ++bj)
; #pragma unroll
;           for (int n = 0; n < 2; ++n) {
;             const int col = colb + bj * 128 + n * 16;
;             const f32x4 gg = *(const f32x4*)(g.ln_g + col), bb = *(const f32x4*)(g.ln_b + col);
;             const f32x4 o = (acc[ai][bj][m][n] - mean) * rs * gg + bb;
;             const size_t idx = (size_t)row * 2048 + col;
;             if (g.outf) *(f32x4*)(g.outf + idx) = o;
;             uint2 ob; ob.x = pk2(o[0], o[1]); ob.y = pk2(o[2], o[3]);
;             *(uint2*)(g.outb + idx) = ob;
;           }
.LBB0_95:
	v_lshl_add_u64 v[102:103], v[140:141], 0, v[118:119]
	s_nop 0
	v_cvt_pk_bf16_f32 v2, v2, v3
	v_cvt_pk_bf16_f32 v3, v4, v5
	v_lshl_add_u64 v[4:5], v[102:103], 1, s[66:67]
	global_store_dwordx2 v[4:5], v[2:3], off
	s_nop 0
	v_sub_f32_e32 v99, v99, v116
	v_sub_f32_e32 v98, v98, v116
	v_sub_f32_e32 v101, v101, v116
	v_sub_f32_e32 v100, v100, v116
	v_mov_b32_e32 v116, v117
	v_pk_mul_f32 v[100:101], v[116:117], v[100:101]
	v_pk_mul_f32 v[98:99], v[112:113], v[98:99]
	s_and_b64 vcc, exec, s[6:7]
	v_pk_fma_f32 v[2:3], v[98:99], v[236:237], v[194:195]
	v_pk_fma_f32 v[4:5], v[100:101], v[238:239], v[196:197]
	s_cbranch_vccnz .LBB0_97
	global_store_dwordx4 v[110:111], v[2:5], off offset:576
.LBB0_97:
	v_lshl_add_u64 v[98:99], v[140:141], 0, v[114:115]
	s_nop 0
	v_cvt_pk_bf16_f32 v2, v2, v3
	v_cvt_pk_bf16_f32 v3, v4, v5
	v_lshl_add_u64 v[4:5], v[98:99], 1, s[66:67]
	global_store_dwordx2 v[4:5], v[2:3], off
	s_nop 0
	ds_read_b64 v[98:99], v0 offset:8448
	s_and_b64 vcc, exec, s[6:7]
	s_waitcnt lgkmcnt(0)
	v_sub_f32_e32 v95, v95, v98
	v_sub_f32_e32 v94, v94, v98
	v_sub_f32_e32 v97, v97, v98
	v_sub_f32_e32 v96, v96, v98
	v_pk_mul_f32 v[96:97], v[98:99], v[96:97] op_sel:[1,0]
	v_pk_mul_f32 v[94:95], v[98:99], v[94:95] op_sel:[1,0]
	v_pk_fma_f32 v[4:5], v[226:227], v[96:97], v[242:243]
	v_pk_fma_f32 v[2:3], v[224:225], v[94:95], v[240:241]
	v_lshl_add_u64 v[94:95], v[150:151], 2, s[88:89]
	s_cbranch_vccnz .LBB0_99
	global_store_dwordx4 v[94:95], v[2:5], off
.LBB0_99:
	s_nop 1
	v_cvt_pk_bf16_f32 v2, v2, v3
	v_cvt_pk_bf16_f32 v3, v4, v5
	global_store_dwordx2 v[148:149], v[2:3], off
	s_nop 0
	v_mov_b32_e32 v96, v99
	v_mov_b32_e32 v97, v99
	v_sub_f32_e32 v105, v91, v98
	v_sub_f32_e32 v104, v90, v98
	v_sub_f32_e32 v93, v93, v98
	v_sub_f32_e32 v92, v92, v98
	v_mov_b32_e32 v90, v99
	v_mov_b32_e32 v91, v99
	v_pk_mul_f32 v[92:93], v[90:91], v[92:93]
	v_pk_mul_f32 v[104:105], v[96:97], v[104:105]
	s_and_b64 vcc, exec, s[6:7]
	v_pk_fma_f32 v[2:3], v[104:105], v[228:229], v[244:245]
	v_pk_fma_f32 v[4:5], v[92:93], v[230:231], v[246:247]
	s_cbranch_vccnz .LBB0_101
	global_store_dwordx4 v[94:95], v[2:5], off offset:64
.LBB0_101:
	v_lshl_add_u64 v[92:93], v[146:147], 0, v[122:123]
	s_nop 0
	v_cvt_pk_bf16_f32 v2, v2, v3
	v_cvt_pk_bf16_f32 v3, v4, v5
	v_lshl_add_u64 v[4:5], v[92:93], 1, s[66:67]
	global_store_dwordx2 v[4:5], v[2:3], off
	s_nop 0
	v_sub_f32_e32 v87, v87, v98
	v_sub_f32_e32 v86, v86, v98
	v_sub_f32_e32 v89, v89, v98
	v_sub_f32_e32 v88, v88, v98
	v_pk_mul_f32 v[88:89], v[90:91], v[88:89]
	v_pk_mul_f32 v[86:87], v[96:97], v[86:87]
	s_and_b64 vcc, exec, s[6:7]
	v_pk_fma_f32 v[2:3], v[86:87], v[232:233], v[248:249]
	v_pk_fma_f32 v[4:5], v[88:89], v[234:235], v[250:251]
	s_cbranch_vccnz .LBB0_103
	global_store_dwordx4 v[94:95], v[2:5], off offset:512
.LBB0_103:
	v_lshl_add_u64 v[86:87], v[146:147], 0, v[118:119]
	s_nop 0
	v_cvt_pk_bf16_f32 v2, v2, v3
	v_cvt_pk_bf16_f32 v3, v4, v5
	v_lshl_add_u64 v[4:5], v[86:87], 1, s[66:67]
	global_store_dwordx2 v[4:5], v[2:3], off
	s_nop 0
	v_sub_f32_e32 v83, v83, v98
	v_sub_f32_e32 v82, v82, v98
	v_sub_f32_e32 v85, v85, v98
	v_sub_f32_e32 v84, v84, v98
	v_mov_b32_e32 v98, v99
	v_pk_mul_f32 v[84:85], v[98:99], v[84:85]
	v_pk_mul_f32 v[82:83], v[96:97], v[82:83]
	s_and_b64 vcc, exec, s[6:7]
	v_pk_fma_f32 v[2:3], v[82:83], v[236:237], v[194:195]
	v_pk_fma_f32 v[4:5], v[84:85], v[238:239], v[196:197]
	s_cbranch_vccnz .LBB0_105
	global_store_dwordx4 v[94:95], v[2:5], off offset:576
.LBB0_105:
	v_lshl_add_u64 v[82:83], v[146:147], 0, v[114:115]
	s_nop 0
	v_cvt_pk_bf16_f32 v2, v2, v3
	v_cvt_pk_bf16_f32 v3, v4, v5
	v_lshl_add_u64 v[4:5], v[82:83], 1, s[66:67]
	global_store_dwordx2 v[4:5], v[2:3], off
	s_nop 0
	ds_read_b64 v[82:83], v0 offset:8576
	s_and_b64 vcc, exec, s[6:7]
	s_waitcnt lgkmcnt(0)
	v_sub_f32_e32 v79, v79, v82
	v_sub_f32_e32 v78, v78, v82
	v_sub_f32_e32 v81, v81, v82
	v_sub_f32_e32 v80, v80, v82
	v_pk_mul_f32 v[80:81], v[82:83], v[80:81] op_sel:[1,0]
	v_pk_mul_f32 v[78:79], v[82:83], v[78:79] op_sel:[1,0]
	v_pk_fma_f32 v[4:5], v[226:227], v[80:81], v[242:243]
	v_pk_fma_f32 v[2:3], v[224:225], v[78:79], v[240:241]
	v_lshl_add_u64 v[78:79], v[156:157], 2, s[88:89]
	s_cbranch_vccnz .LBB0_107
	global_store_dwordx4 v[78:79], v[2:5], off
.LBB0_107:
	s_nop 1
	v_cvt_pk_bf16_f32 v2, v2, v3
	v_cvt_pk_bf16_f32 v3, v4, v5
	global_store_dwordx2 v[154:155], v[2:3], off
	s_nop 0
	v_mov_b32_e32 v80, v83
	v_mov_b32_e32 v81, v83
	v_sub_f32_e32 v89, v75, v82
	v_sub_f32_e32 v88, v74, v82
	v_sub_f32_e32 v77, v77, v82
	v_sub_f32_e32 v76, v76, v82
	v_mov_b32_e32 v74, v83
	v_mov_b32_e32 v75, v83
	v_pk_mul_f32 v[76:77], v[74:75], v[76:77]
	v_pk_mul_f32 v[88:89], v[80:81], v[88:89]
	s_and_b64 vcc, exec, s[6:7]
	v_pk_fma_f32 v[2:3], v[88:89], v[228:229], v[244:245]
	v_pk_fma_f32 v[4:5], v[76:77], v[230:231], v[246:247]
	s_cbranch_vccnz .LBB0_109
	global_store_dwordx4 v[78:79], v[2:5], off offset:64
.LBB0_109:
	v_lshl_add_u64 v[76:77], v[152:153], 0, v[122:123]
	s_nop 0
	v_cvt_pk_bf16_f32 v2, v2, v3
	v_cvt_pk_bf16_f32 v3, v4, v5
	v_lshl_add_u64 v[4:5], v[76:77], 1, s[66:67]
	global_store_dwordx2 v[4:5], v[2:3], off
	s_nop 0
	v_sub_f32_e32 v71, v71, v82
	v_sub_f32_e32 v70, v70, v82
	v_sub_f32_e32 v73, v73, v82
	v_sub_f32_e32 v72, v72, v82
	v_pk_mul_f32 v[72:73], v[74:75], v[72:73]
	v_pk_mul_f32 v[70:71], v[80:81], v[70:71]
	s_and_b64 vcc, exec, s[6:7]
	v_pk_fma_f32 v[2:3], v[70:71], v[232:233], v[248:249]
	v_pk_fma_f32 v[4:5], v[72:73], v[234:235], v[250:251]
	s_cbranch_vccnz .LBB0_111
	global_store_dwordx4 v[78:79], v[2:5], off offset:512
; template <int EPI>
; DI void gemm_unit(const GemmP& g, int pm, int pn) {
;     ...
; #pragma unroll
;     for (int ai = 0; ai < 2; ++ai)
; #pragma unroll
;       for (int m = 0; m < 4; ++m) {
;         const int rl = ai * 128 + wr * 64 + m * 16 + fr;
;         const float mean = mr[rl * 2], rs = mr[rl * 2 + 1];
;         const int row = row0 + ai * 128 + m * 16;
; #pragma unroll
;         for (int bj = 0; bj < 2; ++bj)
; #pragma unroll
;           for (int n = 0; n < 2; ++n) {
;             const int col = colb + bj * 128 + n * 16;
;             const f32x4 gg = *(const f32x4*)(g.ln_g + col), bb = *(const f32x4*)(g.ln_b + col);
;             const f32x4 o = (acc[ai][bj][m][n] - mean) * rs * gg + bb;
;             const size_t idx = (size_t)row * 2048 + col;
;             if (g.outf) *(f32x4*)(g.outf + idx) = o;
;             uint2 ob; ob.x = pk2(o[0], o[1]); ob.y = pk2(o[2], o[3]);
;             *(uint2*)(g.outb + idx) = ob;
;           }
.LBB0_111:
	v_lshl_add_u64 v[70:71], v[152:153], 0, v[118:119]
	s_nop 0
	v_cvt_pk_bf16_f32 v2, v2, v3
	v_cvt_pk_bf16_f32 v3, v4, v5
	v_lshl_add_u64 v[4:5], v[70:71], 1, s[66:67]
	global_store_dwordx2 v[4:5], v[2:3], off
	s_nop 0
	v_sub_f32_e32 v67, v67, v82
	v_sub_f32_e32 v66, v66, v82
	v_sub_f32_e32 v69, v69, v82
	v_sub_f32_e32 v68, v68, v82
	v_mov_b32_e32 v82, v83
	v_pk_mul_f32 v[68:69], v[82:83], v[68:69]
	v_pk_mul_f32 v[66:67], v[80:81], v[66:67]
	s_and_b64 vcc, exec, s[6:7]
	v_pk_fma_f32 v[2:3], v[66:67], v[236:237], v[194:195]
	v_pk_fma_f32 v[4:5], v[68:69], v[238:239], v[196:197]
	s_cbranch_vccnz .LBB0_113
	global_store_dwordx4 v[78:79], v[2:5], off offset:576
.LBB0_113:
	v_lshl_add_u64 v[66:67], v[152:153], 0, v[114:115]
	s_nop 0
	v_cvt_pk_bf16_f32 v2, v2, v3
	v_cvt_pk_bf16_f32 v3, v4, v5
	v_lshl_add_u64 v[4:5], v[66:67], 1, s[66:67]
	global_store_dwordx2 v[4:5], v[2:3], off
	s_nop 0
	v_lshl_add_u32 v66, v206, 3, 0
	ds_read_b64 v[66:67], v66 offset:8192
	s_and_b64 vcc, exec, s[6:7]
	s_waitcnt lgkmcnt(0)
	v_sub_f32_e32 v63, v63, v66
	v_sub_f32_e32 v62, v62, v66
	v_sub_f32_e32 v65, v65, v66
	v_sub_f32_e32 v64, v64, v66
	v_pk_mul_f32 v[64:65], v[66:67], v[64:65] op_sel:[1,0]
	v_pk_mul_f32 v[62:63], v[66:67], v[62:63] op_sel:[1,0]
	v_pk_fma_f32 v[4:5], v[226:227], v[64:65], v[242:243]
	v_pk_fma_f32 v[2:3], v[224:225], v[62:63], v[240:241]
	v_lshl_add_u64 v[62:63], v[164:165], 2, s[88:89]
	s_cbranch_vccnz .LBB0_115
	global_store_dwordx4 v[62:63], v[2:5], off
.LBB0_115:
	s_nop 1
	v_cvt_pk_bf16_f32 v2, v2, v3
	v_cvt_pk_bf16_f32 v3, v4, v5
	global_store_dwordx2 v[162:163], v[2:3], off
	s_nop 0
	v_mov_b32_e32 v64, v67
	v_mov_b32_e32 v65, v67
	v_sub_f32_e32 v73, v59, v66
	v_sub_f32_e32 v72, v58, v66
	v_sub_f32_e32 v61, v61, v66
	v_sub_f32_e32 v60, v60, v66
	v_mov_b32_e32 v58, v67
	v_mov_b32_e32 v59, v67
	v_pk_mul_f32 v[60:61], v[58:59], v[60:61]
	v_pk_mul_f32 v[72:73], v[64:65], v[72:73]
	s_and_b64 vcc, exec, s[6:7]
	v_pk_fma_f32 v[2:3], v[72:73], v[228:229], v[244:245]
	v_pk_fma_f32 v[4:5], v[60:61], v[230:231], v[246:247]
	s_cbranch_vccnz .LBB0_117
	global_store_dwordx4 v[62:63], v[2:5], off offset:64
.LBB0_117:
	v_lshl_add_u64 v[60:61], v[158:159], 0, v[122:123]
	s_nop 0
	v_cvt_pk_bf16_f32 v2, v2, v3
	v_cvt_pk_bf16_f32 v3, v4, v5
	v_lshl_add_u64 v[4:5], v[60:61], 1, s[66:67]
	global_store_dwordx2 v[4:5], v[2:3], off
	s_nop 0
	v_sub_f32_e32 v55, v55, v66
	v_sub_f32_e32 v54, v54, v66
	v_sub_f32_e32 v57, v57, v66
	v_sub_f32_e32 v56, v56, v66
	v_pk_mul_f32 v[56:57], v[58:59], v[56:57]
	v_pk_mul_f32 v[54:55], v[64:65], v[54:55]
	s_and_b64 vcc, exec, s[6:7]
	v_pk_fma_f32 v[2:3], v[54:55], v[232:233], v[248:249]
	v_pk_fma_f32 v[4:5], v[56:57], v[234:235], v[250:251]
	s_cbranch_vccnz .LBB0_119
	global_store_dwordx4 v[62:63], v[2:5], off offset:512
.LBB0_119:
	v_lshl_add_u64 v[54:55], v[158:159], 0, v[118:119]
	s_nop 0
	v_cvt_pk_bf16_f32 v2, v2, v3
	v_cvt_pk_bf16_f32 v3, v4, v5
	v_lshl_add_u64 v[4:5], v[54:55], 1, s[66:67]
	global_store_dwordx2 v[4:5], v[2:3], off
	s_nop 0
	v_sub_f32_e32 v51, v51, v66
	v_sub_f32_e32 v50, v50, v66
	v_sub_f32_e32 v53, v53, v66
	v_sub_f32_e32 v52, v52, v66
	v_mov_b32_e32 v66, v67
	v_pk_mul_f32 v[52:53], v[66:67], v[52:53]
	v_pk_mul_f32 v[50:51], v[64:65], v[50:51]
	s_and_b64 vcc, exec, s[6:7]
	v_pk_fma_f32 v[2:3], v[50:51], v[236:237], v[194:195]
	v_pk_fma_f32 v[4:5], v[52:53], v[238:239], v[196:197]
	s_cbranch_vccnz .LBB0_121
	global_store_dwordx4 v[62:63], v[2:5], off offset:576
.LBB0_121:
	v_lshl_add_u64 v[50:51], v[158:159], 0, v[114:115]
	s_nop 0
	v_cvt_pk_bf16_f32 v2, v2, v3
	v_cvt_pk_bf16_f32 v3, v4, v5
	v_lshl_add_u64 v[4:5], v[50:51], 1, s[66:67]
	global_store_dwordx2 v[4:5], v[2:3], off
	s_nop 0
	ds_read_b64 v[50:51], v0 offset:9344
	s_and_b64 vcc, exec, s[6:7]
	s_waitcnt lgkmcnt(0)
	v_sub_f32_e32 v47, v47, v50
	v_sub_f32_e32 v46, v46, v50
	v_sub_f32_e32 v49, v49, v50
	v_sub_f32_e32 v48, v48, v50
	v_pk_mul_f32 v[48:49], v[50:51], v[48:49] op_sel:[1,0]
	v_pk_mul_f32 v[46:47], v[50:51], v[46:47] op_sel:[1,0]
	v_pk_fma_f32 v[4:5], v[226:227], v[48:49], v[242:243]
	v_pk_fma_f32 v[2:3], v[224:225], v[46:47], v[240:241]
	v_lshl_add_u64 v[46:47], v[170:171], 2, s[88:89]
	s_cbranch_vccnz .LBB0_123
	global_store_dwordx4 v[46:47], v[2:5], off
.LBB0_123:
	s_nop 1
	v_cvt_pk_bf16_f32 v2, v2, v3
	v_cvt_pk_bf16_f32 v3, v4, v5
	global_store_dwordx2 v[168:169], v[2:3], off
	s_nop 0
	v_mov_b32_e32 v48, v51
	v_mov_b32_e32 v49, v51
	v_sub_f32_e32 v57, v43, v50
	v_sub_f32_e32 v56, v42, v50
	v_sub_f32_e32 v45, v45, v50
	v_sub_f32_e32 v44, v44, v50
	v_mov_b32_e32 v42, v51
	v_mov_b32_e32 v43, v51
	v_pk_mul_f32 v[44:45], v[42:43], v[44:45]
	v_pk_mul_f32 v[56:57], v[48:49], v[56:57]
	s_and_b64 vcc, exec, s[6:7]
	v_pk_fma_f32 v[2:3], v[56:57], v[228:229], v[244:245]
	v_pk_fma_f32 v[4:5], v[44:45], v[230:231], v[246:247]
	s_cbranch_vccnz .LBB0_125
	global_store_dwordx4 v[46:47], v[2:5], off offset:64
.LBB0_125:
	v_lshl_add_u64 v[44:45], v[166:167], 0, v[122:123]
	s_nop 0
	v_cvt_pk_bf16_f32 v2, v2, v3
	v_cvt_pk_bf16_f32 v3, v4, v5
	v_lshl_add_u64 v[4:5], v[44:45], 1, s[66:67]
	global_store_dwordx2 v[4:5], v[2:3], off
	s_nop 0
	v_sub_f32_e32 v39, v39, v50
	v_sub_f32_e32 v38, v38, v50
	v_sub_f32_e32 v41, v41, v50
	v_sub_f32_e32 v40, v40, v50
	v_pk_mul_f32 v[40:41], v[42:43], v[40:41]
	v_pk_mul_f32 v[38:39], v[48:49], v[38:39]
	s_and_b64 vcc, exec, s[6:7]
	v_pk_fma_f32 v[2:3], v[38:39], v[232:233], v[248:249]
	v_pk_fma_f32 v[4:5], v[40:41], v[234:235], v[250:251]
	s_cbranch_vccnz .LBB0_127
	global_store_dwordx4 v[46:47], v[2:5], off offset:512
; template <int EPI>
; DI void gemm_unit(const GemmP& g, int pm, int pn) {
;     ...
; #pragma unroll
;     for (int ai = 0; ai < 2; ++ai)
; #pragma unroll
;       for (int m = 0; m < 4; ++m) {
;         const int rl = ai * 128 + wr * 64 + m * 16 + fr;
;         const float mean = mr[rl * 2], rs = mr[rl * 2 + 1];
;         const int row = row0 + ai * 128 + m * 16;
; #pragma unroll
;         for (int bj = 0; bj < 2; ++bj)
; #pragma unroll
;           for (int n = 0; n < 2; ++n) {
;             const int col = colb + bj * 128 + n * 16;
;             const f32x4 gg = *(const f32x4*)(g.ln_g + col), bb = *(const f32x4*)(g.ln_b + col);
;             const f32x4 o = (acc[ai][bj][m][n] - mean) * rs * gg + bb;
;             const size_t idx = (size_t)row * 2048 + col;
;             if (g.outf) *(f32x4*)(g.outf + idx) = o;
;             uint2 ob; ob.x = pk2(o[0], o[1]); ob.y = pk2(o[2], o[3]);
;             *(uint2*)(g.outb + idx) = ob;
;           }
.LBB0_127:
	v_lshl_add_u64 v[38:39], v[166:167], 0, v[118:119]
	s_nop 0
	v_cvt_pk_bf16_f32 v2, v2, v3
	v_cvt_pk_bf16_f32 v3, v4, v5
	v_lshl_add_u64 v[4:5], v[38:39], 1, s[66:67]
	global_store_dwordx2 v[4:5], v[2:3], off
	s_nop 0
	v_sub_f32_e32 v35, v35, v50
	v_sub_f32_e32 v34, v34, v50
	v_sub_f32_e32 v37, v37, v50
	v_sub_f32_e32 v36, v36, v50
	v_mov_b32_e32 v50, v51
	v_pk_mul_f32 v[36:37], v[50:51], v[36:37]
	v_pk_mul_f32 v[34:35], v[48:49], v[34:35]
	s_and_b64 vcc, exec, s[6:7]
	v_pk_fma_f32 v[2:3], v[34:35], v[236:237], v[194:195]
	v_pk_fma_f32 v[4:5], v[36:37], v[238:239], v[196:197]
	s_cbranch_vccnz .LBB0_129
	global_store_dwordx4 v[46:47], v[2:5], off offset:576
.LBB0_129:
	v_lshl_add_u64 v[34:35], v[166:167], 0, v[114:115]
	s_nop 0
	v_cvt_pk_bf16_f32 v2, v2, v3
	v_cvt_pk_bf16_f32 v3, v4, v5
	v_lshl_add_u64 v[4:5], v[34:35], 1, s[66:67]
	global_store_dwordx2 v[4:5], v[2:3], off
	s_nop 0
	ds_read_b64 v[34:35], v0 offset:9472
	s_and_b64 vcc, exec, s[6:7]
	s_waitcnt lgkmcnt(0)
	v_sub_f32_e32 v31, v31, v34
	v_sub_f32_e32 v30, v30, v34
	v_sub_f32_e32 v33, v33, v34
	v_sub_f32_e32 v32, v32, v34
	v_pk_mul_f32 v[32:33], v[34:35], v[32:33] op_sel:[1,0]
	v_pk_mul_f32 v[30:31], v[34:35], v[30:31] op_sel:[1,0]
	v_pk_fma_f32 v[4:5], v[226:227], v[32:33], v[242:243]
	v_pk_fma_f32 v[2:3], v[224:225], v[30:31], v[240:241]
	v_lshl_add_u64 v[30:31], v[174:175], 2, s[88:89]
	s_cbranch_vccnz .LBB0_131
	global_store_dwordx4 v[30:31], v[2:5], off
.LBB0_131:
	s_nop 1
	v_cvt_pk_bf16_f32 v2, v2, v3
	v_cvt_pk_bf16_f32 v3, v4, v5
	global_store_dwordx2 v[172:173], v[2:3], off
	s_nop 0
	v_mov_b32_e32 v32, v35
	v_mov_b32_e32 v33, v35
	v_sub_f32_e32 v41, v27, v34
	v_sub_f32_e32 v40, v26, v34
	v_sub_f32_e32 v29, v29, v34
	v_sub_f32_e32 v28, v28, v34
	v_mov_b32_e32 v26, v35
	v_mov_b32_e32 v27, v35
	v_pk_mul_f32 v[28:29], v[26:27], v[28:29]
	v_pk_mul_f32 v[40:41], v[32:33], v[40:41]
	s_and_b64 vcc, exec, s[6:7]
	v_pk_fma_f32 v[2:3], v[40:41], v[228:229], v[244:245]
	v_pk_fma_f32 v[4:5], v[28:29], v[230:231], v[246:247]
	s_cbranch_vccnz .LBB0_133
	global_store_dwordx4 v[30:31], v[2:5], off offset:64
.LBB0_133:
	v_lshl_add_u64 v[28:29], v[160:161], 0, v[122:123]
	s_nop 0
	v_cvt_pk_bf16_f32 v2, v2, v3
	v_cvt_pk_bf16_f32 v3, v4, v5
	v_lshl_add_u64 v[4:5], v[28:29], 1, s[66:67]
	global_store_dwordx2 v[4:5], v[2:3], off
	s_nop 0
	v_sub_f32_e32 v23, v23, v34
	v_sub_f32_e32 v22, v22, v34
	v_sub_f32_e32 v25, v25, v34
	v_sub_f32_e32 v24, v24, v34
	v_pk_mul_f32 v[24:25], v[26:27], v[24:25]
	v_pk_mul_f32 v[22:23], v[32:33], v[22:23]
	s_and_b64 vcc, exec, s[6:7]
	v_pk_fma_f32 v[2:3], v[22:23], v[232:233], v[248:249]
	v_pk_fma_f32 v[4:5], v[24:25], v[234:235], v[250:251]
	s_cbranch_vccnz .LBB0_135
	global_store_dwordx4 v[30:31], v[2:5], off offset:512
.LBB0_135:
	v_lshl_add_u64 v[22:23], v[160:161], 0, v[118:119]
	s_nop 0
	v_cvt_pk_bf16_f32 v2, v2, v3
	v_cvt_pk_bf16_f32 v3, v4, v5
	v_lshl_add_u64 v[4:5], v[22:23], 1, s[66:67]
	global_store_dwordx2 v[4:5], v[2:3], off
	s_nop 0
	v_sub_f32_e32 v19, v19, v34
	v_sub_f32_e32 v18, v18, v34
	v_sub_f32_e32 v21, v21, v34
	v_sub_f32_e32 v20, v20, v34
	v_mov_b32_e32 v34, v35
	v_pk_mul_f32 v[20:21], v[34:35], v[20:21]
	v_pk_mul_f32 v[18:19], v[32:33], v[18:19]
	s_and_b64 vcc, exec, s[6:7]
	v_pk_fma_f32 v[2:3], v[18:19], v[236:237], v[194:195]
	v_pk_fma_f32 v[4:5], v[20:21], v[238:239], v[196:197]
	s_cbranch_vccnz .LBB0_137
	global_store_dwordx4 v[30:31], v[2:5], off offset:576
.LBB0_137:
	v_lshl_add_u64 v[18:19], v[160:161], 0, v[114:115]
	s_nop 0
	v_cvt_pk_bf16_f32 v2, v2, v3
	v_cvt_pk_bf16_f32 v3, v4, v5
	v_lshl_add_u64 v[4:5], v[18:19], 1, s[66:67]
	global_store_dwordx2 v[4:5], v[2:3], off
	s_nop 0
	ds_read_b64 v[18:19], v0 offset:9600
	s_and_b64 vcc, exec, s[6:7]
	s_waitcnt lgkmcnt(0)
	v_sub_f32_e32 v15, v15, v18
	v_sub_f32_e32 v14, v14, v18
	v_sub_f32_e32 v17, v17, v18
	v_sub_f32_e32 v16, v16, v18
	v_pk_mul_f32 v[16:17], v[18:19], v[16:17] op_sel:[1,0]
	v_pk_mul_f32 v[14:15], v[18:19], v[14:15] op_sel:[1,0]
	v_pk_fma_f32 v[4:5], v[226:227], v[16:17], v[242:243]
	v_pk_fma_f32 v[2:3], v[224:225], v[14:15], v[240:241]
	v_lshl_add_u64 v[14:15], v[180:181], 2, s[88:89]
	s_cbranch_vccnz .LBB0_139
	global_store_dwordx4 v[14:15], v[2:5], off
.LBB0_139:
	s_nop 1
	v_cvt_pk_bf16_f32 v2, v2, v3
	v_cvt_pk_bf16_f32 v3, v4, v5
	global_store_dwordx2 v[178:179], v[2:3], off
	s_nop 0
	v_mov_b32_e32 v16, v19
	v_mov_b32_e32 v17, v19
	v_sub_f32_e32 v25, v11, v18
	v_sub_f32_e32 v24, v10, v18
	v_sub_f32_e32 v13, v13, v18
	v_sub_f32_e32 v12, v12, v18
	v_mov_b32_e32 v10, v19
	v_mov_b32_e32 v11, v19
	v_pk_mul_f32 v[12:13], v[10:11], v[12:13]
	v_pk_mul_f32 v[24:25], v[16:17], v[24:25]
	s_and_b64 vcc, exec, s[6:7]
	v_pk_fma_f32 v[2:3], v[24:25], v[228:229], v[244:245]
	v_pk_fma_f32 v[4:5], v[12:13], v[230:231], v[246:247]
	s_cbranch_vccnz .LBB0_141
	global_store_dwordx4 v[14:15], v[2:5], off offset:64
.LBB0_141:
	v_lshl_add_u64 v[12:13], v[176:177], 0, v[122:123]
	s_nop 0
	v_cvt_pk_bf16_f32 v2, v2, v3
	v_cvt_pk_bf16_f32 v3, v4, v5
	v_lshl_add_u64 v[4:5], v[12:13], 1, s[66:67]
	global_store_dwordx2 v[4:5], v[2:3], off
	s_nop 0
	v_sub_f32_e32 v7, v7, v18
	v_sub_f32_e32 v6, v6, v18
	v_sub_f32_e32 v9, v9, v18
	v_sub_f32_e32 v8, v8, v18
	v_pk_mul_f32 v[8:9], v[10:11], v[8:9]
	v_pk_mul_f32 v[6:7], v[16:17], v[6:7]
	s_and_b64 vcc, exec, s[6:7]
	v_pk_fma_f32 v[2:3], v[6:7], v[232:233], v[248:249]
	v_pk_fma_f32 v[4:5], v[8:9], v[234:235], v[250:251]
	s_cbranch_vccnz .LBB0_143
	global_store_dwordx4 v[14:15], v[2:5], off offset:512
.LBB0_143:
	v_lshl_add_u64 v[6:7], v[176:177], 0, v[118:119]
	s_nop 0
	v_cvt_pk_bf16_f32 v2, v2, v3
	v_cvt_pk_bf16_f32 v3, v4, v5
	v_lshl_add_u64 v[4:5], v[6:7], 1, s[66:67]
	global_store_dwordx2 v[4:5], v[2:3], off
	s_nop 0
	v_sub_f32_e32 v11, v185, v18
	v_sub_f32_e32 v10, v184, v18
	v_sub_f32_e32 v13, v183, v18
	v_sub_f32_e32 v12, v182, v18
	v_mov_b32_e32 v18, v19
	v_pk_mul_f32 v[12:13], v[18:19], v[12:13]
	v_pk_mul_f32 v[10:11], v[16:17], v[10:11]
	s_and_b64 vcc, exec, s[6:7]
	v_pk_fma_f32 v[2:3], v[10:11], v[236:237], v[194:195]
	v_pk_fma_f32 v[4:5], v[12:13], v[238:239], v[196:197]
	s_cbranch_vccnz .LBB0_42
	global_store_dwordx4 v[14:15], v[2:5], off offset:576
	s_branch .LBB0_42

; template <int EPI>
; DI void gemm_unit(const GemmP& g, int pm, int pn) {
;     ...
; #pragma unroll
;     for (int ai = 0; ai < 2; ++ai)
; #pragma unroll
;       for (int m = 0; m < 4; ++m) {
;         const int rl = ai * 128 + wr * 64 + m * 16 + fr;
;         const float mean = mr[rl * 2], rs = mr[rl * 2 + 1];
;         const int row = row0 + ai * 128 + m * 16;
; #pragma unroll
;         for (int bj = 0; bj < 2; ++bj)
; #pragma unroll
;           for (int n = 0; n < 2; ++n) {
;             const int col = colb + bj * 128 + n * 16;
;             const f32x4 gg = *(const f32x4*)(g.ln_g + col), bb = *(const f32x4*)(g.ln_b + col);
;             const f32x4 o = (acc[ai][bj][m][n] - mean) * rs * gg + bb;
;             const size_t idx = (size_t)row * 2048 + col;
;             if (g.outf) *(f32x4*)(g.outf + idx) = o;
;             uint2 ob; ob.x = pk2(o[0], o[1]); ob.y = pk2(o[2], o[3]);
;             *(uint2*)(g.outb + idx) = ob;
;           }
;       }
.LBB0_162:
	s_or_b64 exec, exec, s[6:7]
	v_lshlrev_b64 v[134:135], 2, v[134:135]
	v_lshl_add_u64 v[130:131], s[8:9], 0, v[134:135]
	v_lshl_add_u64 v[134:135], s[10:11], 0, v[134:135]
	global_load_dwordx4 v[224:227], v[130:131], off
	global_load_dwordx4 v[228:231], v[130:131], off offset:64
	global_load_dwordx4 v[232:235], v[130:131], off offset:512
	global_load_dwordx4 v[236:239], v[130:131], off offset:576
	global_load_dwordx4 v[240:243], v[134:135], off
	global_load_dwordx4 v[244:247], v[134:135], off offset:64
	global_load_dwordx4 v[248:251], v[134:135], off offset:512
	global_load_dwordx4 v[194:197], v[134:135], off offset:576
	s_waitcnt lgkmcnt(0)
	s_barrier
	s_waitcnt vmcnt(0)
	v_lshl_add_u32 v0, v0, 3, 0
	v_add_u32_e32 v162, 0x2000, v0
	ds_read2_b64 v[158:161], v162 offset1:16
	s_mov_b32 s27, 32
	s_mov_b64 s[24:25], 0
	s_and_b64 vcc, exec, s[22:23]
	s_waitcnt lgkmcnt(0)
	v_sub_f32_e32 v129, v129, v158
	v_sub_f32_e32 v128, v128, v158
	v_sub_f32_e32 v127, v127, v158
	v_sub_f32_e32 v126, v126, v158
	v_pk_mul_f32 v[126:127], v[158:159], v[126:127] op_sel:[1,0]
	v_pk_mul_f32 v[128:129], v[158:159], v[128:129] op_sel:[1,0]
	v_sub_f32_e32 v125, v125, v158
	v_sub_f32_e32 v124, v124, v158
	v_sub_f32_e32 v123, v123, v158
	v_sub_f32_e32 v122, v122, v158
	v_pk_mul_f32 v[122:123], v[158:159], v[122:123] op_sel:[1,0]
	v_pk_mul_f32 v[124:125], v[158:159], v[124:125] op_sel:[1,0]
	v_sub_f32_e32 v121, v121, v158
	v_sub_f32_e32 v120, v120, v158
	v_sub_f32_e32 v119, v119, v158
	v_sub_f32_e32 v118, v118, v158
	v_pk_mul_f32 v[118:119], v[158:159], v[118:119] op_sel:[1,0]
	v_pk_mul_f32 v[120:121], v[158:159], v[120:121] op_sel:[1,0]
	v_sub_f32_e32 v117, v117, v158
	v_sub_f32_e32 v116, v116, v158
	v_sub_f32_e32 v115, v115, v158
	v_sub_f32_e32 v114, v114, v158
	v_pk_mul_f32 v[114:115], v[158:159], v[114:115] op_sel:[1,0]
	v_pk_mul_f32 v[116:117], v[158:159], v[116:117] op_sel:[1,0]
	v_sub_f32_e32 v113, v113, v160
	v_sub_f32_e32 v112, v112, v160
	v_sub_f32_e32 v111, v111, v160
	v_sub_f32_e32 v110, v110, v160
	v_pk_mul_f32 v[110:111], v[160:161], v[110:111] op_sel:[1,0]
	v_pk_mul_f32 v[112:113], v[160:161], v[112:113] op_sel:[1,0]
	v_sub_f32_e32 v109, v109, v160
	v_sub_f32_e32 v108, v108, v160
	v_sub_f32_e32 v107, v107, v160
	v_sub_f32_e32 v106, v106, v160
	v_pk_mul_f32 v[106:107], v[160:161], v[106:107] op_sel:[1,0]
	v_pk_mul_f32 v[108:109], v[160:161], v[108:109] op_sel:[1,0]
	v_sub_f32_e32 v105, v105, v160
	v_sub_f32_e32 v104, v104, v160
	v_sub_f32_e32 v103, v103, v160
	v_sub_f32_e32 v102, v102, v160
	v_pk_mul_f32 v[102:103], v[160:161], v[102:103] op_sel:[1,0]
	v_pk_mul_f32 v[104:105], v[160:161], v[104:105] op_sel:[1,0]
	v_sub_f32_e32 v101, v101, v160
	v_sub_f32_e32 v100, v100, v160
	v_sub_f32_e32 v99, v99, v160
	v_sub_f32_e32 v98, v98, v160
	v_pk_mul_f32 v[98:99], v[160:161], v[98:99] op_sel:[1,0]
	v_pk_mul_f32 v[100:101], v[160:161], v[100:101] op_sel:[1,0]
	v_pk_fma_f32 v[128:129], v[226:227], v[128:129], v[242:243]
	v_pk_fma_f32 v[126:127], v[224:225], v[126:127], v[240:241]
	s_nop 0
	v_cvt_pk_bf16_f32 v126, v126, v127
	v_cvt_pk_bf16_f32 v127, v128, v129
	global_store_dwordx2 v[132:133], v[126:127], off
	s_nop 0
	v_pk_fma_f32 v[124:125], v[124:125], v[230:231], v[246:247]
	v_pk_fma_f32 v[122:123], v[122:123], v[228:229], v[244:245]
	s_nop 0
	v_cvt_pk_bf16_f32 v122, v122, v123
	v_cvt_pk_bf16_f32 v123, v124, v125
	global_store_dwordx2 v[132:133], v[122:123], off offset:32
	s_nop 0
	v_pk_fma_f32 v[120:121], v[120:121], v[234:235], v[250:251]
	v_pk_fma_f32 v[118:119], v[118:119], v[232:233], v[248:249]
	s_nop 0
	v_cvt_pk_bf16_f32 v118, v118, v119
	v_cvt_pk_bf16_f32 v119, v120, v121
	global_store_dwordx2 v[132:133], v[118:119], off offset:256
	s_nop 0
	v_pk_fma_f32 v[116:117], v[116:117], v[238:239], v[196:197]
	v_pk_fma_f32 v[114:115], v[114:115], v[236:237], v[194:195]
	s_nop 0
	v_cvt_pk_bf16_f32 v114, v114, v115
	v_cvt_pk_bf16_f32 v115, v116, v117
	global_store_dwordx2 v[132:133], v[114:115], off offset:288
	s_nop 0
	v_pk_fma_f32 v[112:113], v[226:227], v[112:113], v[242:243]
	v_pk_fma_f32 v[110:111], v[224:225], v[110:111], v[240:241]
	s_nop 0
	v_cvt_pk_bf16_f32 v110, v110, v111
	v_cvt_pk_bf16_f32 v111, v112, v113
	global_store_dwordx2 v[136:137], v[110:111], off
	s_nop 0
	v_pk_fma_f32 v[108:109], v[108:109], v[230:231], v[246:247]
	v_pk_fma_f32 v[106:107], v[106:107], v[228:229], v[244:245]
	s_nop 0
	v_cvt_pk_bf16_f32 v106, v106, v107
	v_cvt_pk_bf16_f32 v107, v108, v109
	global_store_dwordx2 v[136:137], v[106:107], off offset:32
	s_nop 0
	v_pk_fma_f32 v[104:105], v[104:105], v[234:235], v[250:251]
	v_pk_fma_f32 v[102:103], v[102:103], v[232:233], v[248:249]
	s_nop 0
	v_cvt_pk_bf16_f32 v102, v102, v103
	v_cvt_pk_bf16_f32 v103, v104, v105
	global_store_dwordx2 v[136:137], v[102:103], off offset:256
	s_nop 0
	v_pk_fma_f32 v[100:101], v[100:101], v[238:239], v[196:197]
	v_pk_fma_f32 v[98:99], v[98:99], v[236:237], v[194:195]
	s_nop 0
	v_cvt_pk_bf16_f32 v98, v98, v99
	v_cvt_pk_bf16_f32 v99, v100, v101
	global_store_dwordx2 v[136:137], v[98:99], off offset:288
	s_nop 0
	ds_read2_b64 v[106:109], v162 offset0:32 offset1:48
	s_waitcnt lgkmcnt(0)
; template <int EPI>
; DI void gemm_unit(const GemmP& g, int pm, int pn) {
;     ...
; #pragma unroll
;     for (int ai = 0; ai < 2; ++ai)
; #pragma unroll
;       for (int m = 0; m < 4; ++m) {
;         const int rl = ai * 128 + wr * 64 + m * 16 + fr;
;         const float mean = mr[rl * 2], rs = mr[rl * 2 + 1];
;         const int row = row0 + ai * 128 + m * 16;
; #pragma unroll
;         for (int bj = 0; bj < 2; ++bj)
; #pragma unroll
;           for (int n = 0; n < 2; ++n) {
;             const int col = colb + bj * 128 + n * 16;
;             const f32x4 gg = *(const f32x4*)(g.ln_g + col), bb = *(const f32x4*)(g.ln_b + col);
;             const f32x4 o = (acc[ai][bj][m][n] - mean) * rs * gg + bb;
;             const size_t idx = (size_t)row * 2048 + col;
;             if (g.outf) *(f32x4*)(g.outf + idx) = o;
;             uint2 ob; ob.x = pk2(o[0], o[1]); ob.y = pk2(o[2], o[3]);
;             *(uint2*)(g.outb + idx) = ob;
;           }
;       }
	v_sub_f32_e32 v97, v97, v106
	v_sub_f32_e32 v96, v96, v106
	v_sub_f32_e32 v95, v95, v106
	v_sub_f32_e32 v94, v94, v106
	v_pk_mul_f32 v[94:95], v[106:107], v[94:95] op_sel:[1,0]
	v_pk_mul_f32 v[96:97], v[106:107], v[96:97] op_sel:[1,0]
	v_sub_f32_e32 v93, v93, v106
	v_sub_f32_e32 v92, v92, v106
	v_sub_f32_e32 v91, v91, v106
	v_sub_f32_e32 v90, v90, v106
	v_pk_mul_f32 v[90:91], v[106:107], v[90:91] op_sel:[1,0]
	v_pk_mul_f32 v[92:93], v[106:107], v[92:93] op_sel:[1,0]
	v_sub_f32_e32 v89, v89, v106
	v_sub_f32_e32 v88, v88, v106
	v_sub_f32_e32 v87, v87, v106
	v_sub_f32_e32 v86, v86, v106
	v_pk_mul_f32 v[86:87], v[106:107], v[86:87] op_sel:[1,0]
	v_pk_mul_f32 v[88:89], v[106:107], v[88:89] op_sel:[1,0]
	v_sub_f32_e32 v85, v85, v106
	v_sub_f32_e32 v84, v84, v106
	v_sub_f32_e32 v83, v83, v106
	v_sub_f32_e32 v82, v82, v106
	v_pk_mul_f32 v[82:83], v[106:107], v[82:83] op_sel:[1,0]
	v_pk_mul_f32 v[84:85], v[106:107], v[84:85] op_sel:[1,0]
	v_sub_f32_e32 v81, v81, v108
	v_sub_f32_e32 v80, v80, v108
	v_sub_f32_e32 v79, v79, v108
	v_sub_f32_e32 v78, v78, v108
	v_pk_mul_f32 v[78:79], v[108:109], v[78:79] op_sel:[1,0]
	v_pk_mul_f32 v[80:81], v[108:109], v[80:81] op_sel:[1,0]
	v_sub_f32_e32 v77, v77, v108
	v_sub_f32_e32 v76, v76, v108
	v_sub_f32_e32 v75, v75, v108
	v_sub_f32_e32 v74, v74, v108
	v_pk_mul_f32 v[74:75], v[108:109], v[74:75] op_sel:[1,0]
	v_pk_mul_f32 v[76:77], v[108:109], v[76:77] op_sel:[1,0]
	v_sub_f32_e32 v73, v73, v108
	v_sub_f32_e32 v72, v72, v108
	v_sub_f32_e32 v71, v71, v108
	v_sub_f32_e32 v70, v70, v108
	v_pk_mul_f32 v[70:71], v[108:109], v[70:71] op_sel:[1,0]
	v_pk_mul_f32 v[72:73], v[108:109], v[72:73] op_sel:[1,0]
	v_sub_f32_e32 v69, v69, v108
	v_sub_f32_e32 v68, v68, v108
	v_sub_f32_e32 v67, v67, v108
	v_sub_f32_e32 v66, v66, v108
	v_pk_mul_f32 v[66:67], v[108:109], v[66:67] op_sel:[1,0]
	v_pk_mul_f32 v[68:69], v[108:109], v[68:69] op_sel:[1,0]
	v_pk_fma_f32 v[96:97], v[226:227], v[96:97], v[242:243]
	v_pk_fma_f32 v[94:95], v[224:225], v[94:95], v[240:241]
	s_nop 0
	v_cvt_pk_bf16_f32 v94, v94, v95
	v_cvt_pk_bf16_f32 v95, v96, v97
	global_store_dwordx2 v[138:139], v[94:95], off
	s_nop 0
	v_pk_fma_f32 v[92:93], v[92:93], v[230:231], v[246:247]
	v_pk_fma_f32 v[90:91], v[90:91], v[228:229], v[244:245]
	s_nop 0
	v_cvt_pk_bf16_f32 v90, v90, v91
	v_cvt_pk_bf16_f32 v91, v92, v93
	global_store_dwordx2 v[138:139], v[90:91], off offset:32
	s_nop 0
	v_pk_fma_f32 v[88:89], v[88:89], v[234:235], v[250:251]
	v_pk_fma_f32 v[86:87], v[86:87], v[232:233], v[248:249]
	s_nop 0
	v_cvt_pk_bf16_f32 v86, v86, v87
	v_cvt_pk_bf16_f32 v87, v88, v89
	global_store_dwordx2 v[138:139], v[86:87], off offset:256
	s_nop 0
	v_pk_fma_f32 v[84:85], v[84:85], v[238:239], v[196:197]
	v_pk_fma_f32 v[82:83], v[82:83], v[236:237], v[194:195]
	s_nop 0
	v_cvt_pk_bf16_f32 v82, v82, v83
	v_cvt_pk_bf16_f32 v83, v84, v85
	global_store_dwordx2 v[138:139], v[82:83], off offset:288
	s_nop 0
	v_pk_fma_f32 v[80:81], v[226:227], v[80:81], v[242:243]
	v_pk_fma_f32 v[78:79], v[224:225], v[78:79], v[240:241]
	s_nop 0
	v_cvt_pk_bf16_f32 v78, v78, v79
	v_cvt_pk_bf16_f32 v79, v80, v81
	global_store_dwordx2 v[140:141], v[78:79], off
	s_nop 0
	v_pk_fma_f32 v[76:77], v[76:77], v[230:231], v[246:247]
	v_pk_fma_f32 v[74:75], v[74:75], v[228:229], v[244:245]
	s_nop 0
	v_cvt_pk_bf16_f32 v74, v74, v75
	v_cvt_pk_bf16_f32 v75, v76, v77
	global_store_dwordx2 v[140:141], v[74:75], off offset:32
	s_nop 0
	v_pk_fma_f32 v[72:73], v[72:73], v[234:235], v[250:251]
	v_pk_fma_f32 v[70:71], v[70:71], v[232:233], v[248:249]
	s_nop 0
	v_cvt_pk_bf16_f32 v70, v70, v71
	v_cvt_pk_bf16_f32 v71, v72, v73
	global_store_dwordx2 v[140:141], v[70:71], off offset:256
	s_nop 0
	v_pk_fma_f32 v[68:69], v[68:69], v[238:239], v[196:197]
	v_pk_fma_f32 v[66:67], v[66:67], v[236:237], v[194:195]
	v_lshl_add_u32 v74, v171, 3, 0
	v_cvt_pk_bf16_f32 v66, v66, v67
	v_cvt_pk_bf16_f32 v67, v68, v69
	global_store_dwordx2 v[140:141], v[66:67], off offset:288
	s_nop 0
	ds_read_b64 v[74:75], v74 offset:8192
	s_waitcnt lgkmcnt(0)
	v_sub_f32_e32 v65, v65, v74
	v_sub_f32_e32 v64, v64, v74
	v_sub_f32_e32 v63, v63, v74
	v_sub_f32_e32 v62, v62, v74
	v_pk_mul_f32 v[62:63], v[74:75], v[62:63] op_sel:[1,0]
	v_pk_mul_f32 v[64:65], v[74:75], v[64:65] op_sel:[1,0]
	v_sub_f32_e32 v61, v61, v74
	v_sub_f32_e32 v60, v60, v74
	v_sub_f32_e32 v59, v59, v74
	v_sub_f32_e32 v58, v58, v74
	v_pk_mul_f32 v[58:59], v[74:75], v[58:59] op_sel:[1,0]
	v_pk_mul_f32 v[60:61], v[74:75], v[60:61] op_sel:[1,0]
	v_sub_f32_e32 v57, v57, v74
	v_sub_f32_e32 v56, v56, v74
	v_sub_f32_e32 v55, v55, v74
	v_sub_f32_e32 v54, v54, v74
	v_pk_mul_f32 v[54:55], v[74:75], v[54:55] op_sel:[1,0]
	v_pk_mul_f32 v[56:57], v[74:75], v[56:57] op_sel:[1,0]
	v_sub_f32_e32 v53, v53, v74
	v_sub_f32_e32 v52, v52, v74
	v_sub_f32_e32 v51, v51, v74
	v_sub_f32_e32 v50, v50, v74
	v_pk_mul_f32 v[50:51], v[74:75], v[50:51] op_sel:[1,0]
	v_pk_mul_f32 v[52:53], v[74:75], v[52:53] op_sel:[1,0]
	v_pk_fma_f32 v[64:65], v[226:227], v[64:65], v[242:243]
	v_pk_fma_f32 v[62:63], v[224:225], v[62:63], v[240:241]
	s_nop 0
	v_cvt_pk_bf16_f32 v62, v62, v63
	v_cvt_pk_bf16_f32 v63, v64, v65
	global_store_dwordx2 v[144:145], v[62:63], off
	s_nop 0
	v_pk_fma_f32 v[60:61], v[60:61], v[230:231], v[246:247]
	v_pk_fma_f32 v[58:59], v[58:59], v[228:229], v[244:245]
	s_nop 0
	v_cvt_pk_bf16_f32 v58, v58, v59
	v_cvt_pk_bf16_f32 v59, v60, v61
	global_store_dwordx2 v[144:145], v[58:59], off offset:32
	s_nop 0
	v_pk_fma_f32 v[56:57], v[56:57], v[234:235], v[250:251]
	v_pk_fma_f32 v[54:55], v[54:55], v[232:233], v[248:249]
	s_nop 0
	v_cvt_pk_bf16_f32 v54, v54, v55
	v_cvt_pk_bf16_f32 v55, v56, v57
	global_store_dwordx2 v[144:145], v[54:55], off offset:256
	s_nop 0
	v_pk_fma_f32 v[52:53], v[52:53], v[238:239], v[196:197]
	v_pk_fma_f32 v[50:51], v[50:51], v[236:237], v[194:195]
	s_nop 0
	v_cvt_pk_bf16_f32 v50, v50, v51
	v_cvt_pk_bf16_f32 v51, v52, v53
	global_store_dwordx2 v[144:145], v[50:51], off offset:288
	s_nop 0
	ds_read2_b64 v[58:61], v162 offset0:144 offset1:160
	s_waitcnt lgkmcnt(0)
; template <int EPI>
; DI void gemm_unit(const GemmP& g, int pm, int pn) {
;     ...
; #pragma unroll
;     for (int ai = 0; ai < 2; ++ai)
; #pragma unroll
;       for (int m = 0; m < 4; ++m) {
;         const int rl = ai * 128 + wr * 64 + m * 16 + fr;
;         const float mean = mr[rl * 2], rs = mr[rl * 2 + 1];
;         const int row = row0 + ai * 128 + m * 16;
; #pragma unroll
;         for (int bj = 0; bj < 2; ++bj)
; #pragma unroll
;           for (int n = 0; n < 2; ++n) {
;             const int col = colb + bj * 128 + n * 16;
;             const f32x4 gg = *(const f32x4*)(g.ln_g + col), bb = *(const f32x4*)(g.ln_b + col);
;             const f32x4 o = (acc[ai][bj][m][n] - mean) * rs * gg + bb;
;             const size_t idx = (size_t)row * 2048 + col;
;             if (g.outf) *(f32x4*)(g.outf + idx) = o;
;             uint2 ob; ob.x = pk2(o[0], o[1]); ob.y = pk2(o[2], o[3]);
;             *(uint2*)(g.outb + idx) = ob;
;           }
;       }
	v_sub_f32_e32 v49, v49, v58
	v_sub_f32_e32 v48, v48, v58
	v_sub_f32_e32 v47, v47, v58
	v_sub_f32_e32 v46, v46, v58
	v_pk_mul_f32 v[46:47], v[58:59], v[46:47] op_sel:[1,0]
	v_pk_mul_f32 v[48:49], v[58:59], v[48:49] op_sel:[1,0]
	v_sub_f32_e32 v45, v45, v58
	v_sub_f32_e32 v44, v44, v58
	v_sub_f32_e32 v43, v43, v58
	v_sub_f32_e32 v42, v42, v58
	v_pk_mul_f32 v[42:43], v[58:59], v[42:43] op_sel:[1,0]
	v_pk_mul_f32 v[44:45], v[58:59], v[44:45] op_sel:[1,0]
	v_sub_f32_e32 v41, v41, v58
	v_sub_f32_e32 v40, v40, v58
	v_sub_f32_e32 v39, v39, v58
	v_sub_f32_e32 v38, v38, v58
	v_pk_mul_f32 v[38:39], v[58:59], v[38:39] op_sel:[1,0]
	v_pk_mul_f32 v[40:41], v[58:59], v[40:41] op_sel:[1,0]
	v_sub_f32_e32 v37, v37, v58
	v_sub_f32_e32 v36, v36, v58
	v_sub_f32_e32 v35, v35, v58
	v_sub_f32_e32 v34, v34, v58
	v_pk_mul_f32 v[34:35], v[58:59], v[34:35] op_sel:[1,0]
	v_pk_mul_f32 v[36:37], v[58:59], v[36:37] op_sel:[1,0]
	v_sub_f32_e32 v33, v33, v60
	v_sub_f32_e32 v32, v32, v60
	v_sub_f32_e32 v31, v31, v60
	v_sub_f32_e32 v30, v30, v60
	v_pk_mul_f32 v[30:31], v[60:61], v[30:31] op_sel:[1,0]
	v_pk_mul_f32 v[32:33], v[60:61], v[32:33] op_sel:[1,0]
	v_sub_f32_e32 v29, v29, v60
	v_sub_f32_e32 v28, v28, v60
	v_sub_f32_e32 v27, v27, v60
	v_sub_f32_e32 v26, v26, v60
	v_pk_mul_f32 v[26:27], v[60:61], v[26:27] op_sel:[1,0]
	v_pk_mul_f32 v[28:29], v[60:61], v[28:29] op_sel:[1,0]
	v_sub_f32_e32 v25, v25, v60
	v_sub_f32_e32 v24, v24, v60
	v_sub_f32_e32 v23, v23, v60
	v_sub_f32_e32 v22, v22, v60
	v_pk_mul_f32 v[22:23], v[60:61], v[22:23] op_sel:[1,0]
	v_pk_mul_f32 v[24:25], v[60:61], v[24:25] op_sel:[1,0]
	v_sub_f32_e32 v21, v21, v60
	v_sub_f32_e32 v20, v20, v60
	v_sub_f32_e32 v19, v19, v60
	v_sub_f32_e32 v18, v18, v60
	v_pk_mul_f32 v[18:19], v[60:61], v[18:19] op_sel:[1,0]
	v_pk_mul_f32 v[20:21], v[60:61], v[20:21] op_sel:[1,0]
	v_pk_fma_f32 v[48:49], v[226:227], v[48:49], v[242:243]
	v_pk_fma_f32 v[46:47], v[224:225], v[46:47], v[240:241]
	s_nop 0
	v_cvt_pk_bf16_f32 v46, v46, v47
	v_cvt_pk_bf16_f32 v47, v48, v49
	global_store_dwordx2 v[146:147], v[46:47], off
	s_nop 0
	v_pk_fma_f32 v[44:45], v[44:45], v[230:231], v[246:247]
	v_pk_fma_f32 v[42:43], v[42:43], v[228:229], v[244:245]
	s_nop 0
	v_cvt_pk_bf16_f32 v42, v42, v43
	v_cvt_pk_bf16_f32 v43, v44, v45
	global_store_dwordx2 v[146:147], v[42:43], off offset:32
	s_nop 0
	v_pk_fma_f32 v[40:41], v[40:41], v[234:235], v[250:251]
	v_pk_fma_f32 v[38:39], v[38:39], v[232:233], v[248:249]
	s_nop 0
	v_cvt_pk_bf16_f32 v38, v38, v39
	v_cvt_pk_bf16_f32 v39, v40, v41
	global_store_dwordx2 v[146:147], v[38:39], off offset:256
	s_nop 0
	v_pk_fma_f32 v[36:37], v[36:37], v[238:239], v[196:197]
	v_pk_fma_f32 v[34:35], v[34:35], v[236:237], v[194:195]
	s_nop 0
	v_cvt_pk_bf16_f32 v34, v34, v35
	v_cvt_pk_bf16_f32 v35, v36, v37
	global_store_dwordx2 v[146:147], v[34:35], off offset:288
	s_nop 0
	v_pk_fma_f32 v[32:33], v[226:227], v[32:33], v[242:243]
	v_pk_fma_f32 v[30:31], v[224:225], v[30:31], v[240:241]
	s_nop 0
	v_cvt_pk_bf16_f32 v30, v30, v31
	v_cvt_pk_bf16_f32 v31, v32, v33
	global_store_dwordx2 v[142:143], v[30:31], off
	s_nop 0
	v_pk_fma_f32 v[28:29], v[28:29], v[230:231], v[246:247]
	v_pk_fma_f32 v[26:27], v[26:27], v[228:229], v[244:245]
	s_nop 0
	v_cvt_pk_bf16_f32 v26, v26, v27
	v_cvt_pk_bf16_f32 v27, v28, v29
	global_store_dwordx2 v[142:143], v[26:27], off offset:32
	s_nop 0
	v_pk_fma_f32 v[24:25], v[24:25], v[234:235], v[250:251]
	v_pk_fma_f32 v[22:23], v[22:23], v[232:233], v[248:249]
	s_nop 0
	v_cvt_pk_bf16_f32 v22, v22, v23
	v_cvt_pk_bf16_f32 v23, v24, v25
	global_store_dwordx2 v[142:143], v[22:23], off offset:256
	s_nop 0
	v_pk_fma_f32 v[20:21], v[20:21], v[238:239], v[196:197]
	v_pk_fma_f32 v[18:19], v[18:19], v[236:237], v[194:195]
	s_nop 0
	v_cvt_pk_bf16_f32 v18, v18, v19
	v_cvt_pk_bf16_f32 v19, v20, v21
	global_store_dwordx2 v[142:143], v[18:19], off offset:288
	s_nop 0
	ds_read_b64 v[26:27], v0 offset:9600
	s_waitcnt lgkmcnt(0)
	v_sub_f32_e32 v17, v17, v26
	v_sub_f32_e32 v16, v16, v26
	v_sub_f32_e32 v15, v15, v26
	v_sub_f32_e32 v14, v14, v26
	v_pk_mul_f32 v[14:15], v[26:27], v[14:15] op_sel:[1,0]
	v_pk_mul_f32 v[16:17], v[26:27], v[16:17] op_sel:[1,0]
	v_sub_f32_e32 v13, v13, v26
	v_sub_f32_e32 v12, v12, v26
	v_sub_f32_e32 v11, v11, v26
	v_sub_f32_e32 v10, v10, v26
	v_pk_mul_f32 v[10:11], v[26:27], v[10:11] op_sel:[1,0]
	v_pk_mul_f32 v[12:13], v[26:27], v[12:13] op_sel:[1,0]
	v_sub_f32_e32 v9, v9, v26
	v_sub_f32_e32 v8, v8, v26
	v_sub_f32_e32 v7, v7, v26
	v_sub_f32_e32 v6, v6, v26
	v_pk_mul_f32 v[6:7], v[26:27], v[6:7] op_sel:[1,0]
	v_pk_mul_f32 v[8:9], v[26:27], v[8:9] op_sel:[1,0]
	v_sub_f32_e32 v5, v5, v26
	v_sub_f32_e32 v4, v4, v26
	v_sub_f32_e32 v3, v3, v26
	v_sub_f32_e32 v2, v2, v26
	v_pk_mul_f32 v[2:3], v[26:27], v[2:3] op_sel:[1,0]
	v_pk_mul_f32 v[4:5], v[26:27], v[4:5] op_sel:[1,0]
	v_pk_fma_f32 v[16:17], v[226:227], v[16:17], v[242:243]
	v_pk_fma_f32 v[14:15], v[224:225], v[14:15], v[240:241]
	s_nop 0
	v_cvt_pk_bf16_f32 v14, v14, v15
	v_cvt_pk_bf16_f32 v15, v16, v17
	global_store_dwordx2 v[148:149], v[14:15], off
	s_nop 0
	v_pk_fma_f32 v[12:13], v[12:13], v[230:231], v[246:247]
	v_pk_fma_f32 v[10:11], v[10:11], v[228:229], v[244:245]
	s_nop 0
	v_cvt_pk_bf16_f32 v10, v10, v11
	v_cvt_pk_bf16_f32 v11, v12, v13
	global_store_dwordx2 v[148:149], v[10:11], off offset:32
	s_nop 0
	v_pk_fma_f32 v[8:9], v[8:9], v[234:235], v[250:251]
	v_pk_fma_f32 v[6:7], v[6:7], v[232:233], v[248:249]
	s_nop 0
	v_cvt_pk_bf16_f32 v6, v6, v7
	v_cvt_pk_bf16_f32 v7, v8, v9
	global_store_dwordx2 v[148:149], v[6:7], off offset:256
	s_nop 0
	v_pk_fma_f32 v[4:5], v[4:5], v[238:239], v[196:197]
	v_pk_fma_f32 v[2:3], v[2:3], v[236:237], v[194:195]
	s_nop 0
	v_cvt_pk_bf16_f32 v2, v2, v3
	v_cvt_pk_bf16_f32 v3, v4, v5
	global_store_dwordx2 v[148:149], v[2:3], off offset:288
	s_barrier
	s_cbranch_vccnz .LBB0_200

; template <int EPI>
; DI void gemm_unit(const GemmP& g, int pm, int pn) {
;     ...
; #pragma unroll
;     for (int ai = 0; ai < 2; ++ai)
; #pragma unroll
;       for (int m = 0; m < 4; ++m) {
;         const int rl = ai * 128 + wr * 64 + m * 16 + fr;
;         const float mean = mr[rl * 2], rs = mr[rl * 2 + 1];
;         const int row = row0 + ai * 128 + m * 16;
; #pragma unroll
;         for (int bj = 0; bj < 2; ++bj)
; #pragma unroll
;           for (int n = 0; n < 2; ++n) {
;             const int col = colb + bj * 128 + n * 16;
;             const f32x4 gg = *(const f32x4*)(g.ln_g + col), bb = *(const f32x4*)(g.ln_b + col);
;             const f32x4 o = (acc[ai][bj][m][n] - mean) * rs * gg + bb;
;             const size_t idx = (size_t)row * 2048 + col;
;             if (g.outf) *(f32x4*)(g.outf + idx) = o;
;             uint2 ob; ob.x = pk2(o[0], o[1]); ob.y = pk2(o[2], o[3]);
;             *(uint2*)(g.outb + idx) = ob;
;           }
;       }
.LBB0_296:
	s_or_b64 exec, exec, s[6:7]
	v_lshlrev_b64 v[20:21], 2, v[148:149]
	v_lshl_add_u64 v[18:19], s[10:11], 0, v[20:21]
	v_lshl_add_u64 v[20:21], s[12:13], 0, v[20:21]
	global_load_dwordx4 v[224:227], v[18:19], off
	global_load_dwordx4 v[228:231], v[18:19], off offset:64
	global_load_dwordx4 v[232:235], v[18:19], off offset:512
	global_load_dwordx4 v[236:239], v[18:19], off offset:576
	global_load_dwordx4 v[240:243], v[20:21], off
	global_load_dwordx4 v[244:247], v[20:21], off offset:64
	global_load_dwordx4 v[248:251], v[20:21], off offset:512
	global_load_dwordx4 v[194:197], v[20:21], off offset:576
	s_waitcnt lgkmcnt(0)
	s_barrier
	s_waitcnt vmcnt(0)
	v_lshl_add_u32 v0, v0, 3, 0
	v_add_u32_e32 v24, 0x2000, v0
	ds_read2_b64 v[184:187], v24 offset1:16
	v_lshl_add_u64 v[114:115], v[114:115], 1, s[66:67]
	v_lshl_add_u64 v[98:99], v[98:99], 1, s[66:67]
	v_lshl_add_u32 v25, v189, 3, 0
	v_lshl_add_u64 v[82:83], v[82:83], 1, s[66:67]
	s_waitcnt lgkmcnt(0)
	v_sub_f32_e32 v23, v157, v184
	v_sub_f32_e32 v22, v156, v184
	v_sub_f32_e32 v147, v155, v184
	v_sub_f32_e32 v146, v154, v184
	v_pk_mul_f32 v[146:147], v[184:185], v[146:147] op_sel:[1,0]
	v_pk_mul_f32 v[22:23], v[184:185], v[22:23] op_sel:[1,0]
	v_sub_f32_e32 v133, v133, v184
	v_sub_f32_e32 v132, v132, v184
	v_sub_f32_e32 v131, v131, v184
	v_sub_f32_e32 v130, v130, v184
	v_pk_mul_f32 v[130:131], v[184:185], v[130:131] op_sel:[1,0]
	v_pk_mul_f32 v[132:133], v[184:185], v[132:133] op_sel:[1,0]
	v_sub_f32_e32 v121, v121, v186
	v_sub_f32_e32 v120, v120, v186
	v_sub_f32_e32 v117, v117, v186
	v_sub_f32_e32 v116, v116, v186
	v_pk_mul_f32 v[116:117], v[186:187], v[116:117] op_sel:[1,0]
	v_pk_mul_f32 v[120:121], v[186:187], v[120:121] op_sel:[1,0]
	v_sub_f32_e32 v119, v119, v186
	v_sub_f32_e32 v118, v118, v186
	v_pk_mul_f32 v[118:119], v[186:187], v[118:119] op_sel:[1,0]
	s_mov_b32 s26, 32
	s_mov_b64 s[8:9], 0
	s_and_b64 vcc, exec, s[24:25]
	v_pk_fma_f32 v[22:23], v[226:227], v[22:23], v[242:243]
	v_pk_fma_f32 v[26:27], v[224:225], v[146:147], v[240:241]
	v_lshl_add_u64 v[146:147], v[150:151], 1, s[66:67]
	v_cvt_pk_bf16_f32 v26, v26, v27
	v_cvt_pk_bf16_f32 v27, v22, v23
	global_store_dwordx2 v[152:153], v[26:27], off
	s_nop 0
	v_lshlrev_b64 v[22:23], 1, v[148:149]
	v_lshl_add_u64 v[146:147], v[146:147], 0, v[22:23]
	v_lshl_add_u64 v[114:115], v[114:115], 0, v[22:23]
	v_lshl_add_u64 v[98:99], v[98:99], 0, v[22:23]
	v_lshl_add_u64 v[82:83], v[82:83], 0, v[22:23]
	v_pk_fma_f32 v[28:29], v[132:133], v[230:231], v[246:247]
	v_pk_fma_f32 v[26:27], v[130:131], v[228:229], v[244:245]
	v_sub_f32_e32 v131, v141, v184
	v_cvt_pk_bf16_f32 v26, v26, v27
	v_cvt_pk_bf16_f32 v27, v28, v29
	global_store_dwordx2 v[146:147], v[26:27], off offset:32
	s_nop 0
	v_sub_f32_e32 v130, v140, v184
	v_sub_f32_e32 v133, v137, v184
	v_sub_f32_e32 v132, v136, v184
	v_pk_mul_f32 v[132:133], v[184:185], v[132:133] op_sel:[1,0]
	v_pk_mul_f32 v[130:131], v[184:185], v[130:131] op_sel:[1,0]
	v_pk_fma_f32 v[26:27], v[132:133], v[232:233], v[248:249]
	v_pk_fma_f32 v[28:29], v[130:131], v[234:235], v[250:251]
	v_cvt_pk_bf16_f32 v26, v26, v27
	v_cvt_pk_bf16_f32 v27, v28, v29
	global_store_dwordx2 v[146:147], v[26:27], off offset:256
	s_nop 0
	v_sub_f32_e32 v131, v145, v184
	v_sub_f32_e32 v130, v144, v184
	v_sub_f32_e32 v133, v139, v184
	v_sub_f32_e32 v132, v138, v184
	v_pk_mul_f32 v[132:133], v[184:185], v[132:133] op_sel:[1,0]
	v_pk_mul_f32 v[130:131], v[184:185], v[130:131] op_sel:[1,0]
	v_pk_fma_f32 v[26:27], v[132:133], v[236:237], v[194:195]
	v_pk_fma_f32 v[28:29], v[130:131], v[238:239], v[196:197]
	v_cvt_pk_bf16_f32 v26, v26, v27
	v_cvt_pk_bf16_f32 v27, v28, v29
	global_store_dwordx2 v[146:147], v[26:27], off offset:288
	s_nop 0
	v_sub_f32_e32 v131, v161, v186
	v_sub_f32_e32 v130, v160, v186
	v_sub_f32_e32 v133, v159, v186
	v_sub_f32_e32 v132, v158, v186
	v_pk_mul_f32 v[132:133], v[186:187], v[132:133] op_sel:[1,0]
	v_pk_mul_f32 v[130:131], v[186:187], v[130:131] op_sel:[1,0]
	v_pk_fma_f32 v[26:27], v[224:225], v[132:133], v[240:241]
	v_pk_fma_f32 v[28:29], v[226:227], v[130:131], v[242:243]
	v_cvt_pk_bf16_f32 v26, v26, v27
	v_cvt_pk_bf16_f32 v27, v28, v29
	global_store_dwordx2 v[142:143], v[26:27], off
	s_nop 0
	v_lshl_add_u64 v[130:131], v[134:135], 1, s[66:67]
	v_lshl_add_u64 v[130:131], v[130:131], 0, v[22:23]
	v_pk_fma_f32 v[28:29], v[120:121], v[230:231], v[246:247]
	v_pk_fma_f32 v[26:27], v[116:117], v[228:229], v[244:245]
	v_sub_f32_e32 v117, v125, v186
	v_cvt_pk_bf16_f32 v26, v26, v27
	v_cvt_pk_bf16_f32 v27, v28, v29
	global_store_dwordx2 v[130:131], v[26:27], off offset:32
	s_nop 0
	v_sub_f32_e32 v116, v124, v186
	v_pk_mul_f32 v[116:117], v[186:187], v[116:117] op_sel:[1,0]
	v_pk_fma_f32 v[26:27], v[118:119], v[232:233], v[248:249]
	v_pk_fma_f32 v[28:29], v[116:117], v[234:235], v[250:251]
	v_cvt_pk_bf16_f32 v26, v26, v27
	v_cvt_pk_bf16_f32 v27, v28, v29
	global_store_dwordx2 v[130:131], v[26:27], off offset:256
	s_nop 0
	v_sub_f32_e32 v117, v129, v186
	v_sub_f32_e32 v116, v128, v186
	v_sub_f32_e32 v119, v123, v186
	v_sub_f32_e32 v118, v122, v186
	v_pk_mul_f32 v[118:119], v[186:187], v[118:119] op_sel:[1,0]
	v_pk_mul_f32 v[116:117], v[186:187], v[116:117] op_sel:[1,0]
	v_pk_fma_f32 v[26:27], v[118:119], v[236:237], v[194:195]
	v_pk_fma_f32 v[28:29], v[116:117], v[238:239], v[196:197]
	v_cvt_pk_bf16_f32 v26, v26, v27
	v_cvt_pk_bf16_f32 v27, v28, v29
	global_store_dwordx2 v[130:131], v[26:27], off offset:288
	s_nop 0
	ds_read2_b64 v[116:119], v24 offset0:32 offset1:48
	s_waitcnt lgkmcnt(0)
; template <int EPI>
; DI void gemm_unit(const GemmP& g, int pm, int pn) {
;     ...
; #pragma unroll
;     for (int ai = 0; ai < 2; ++ai)
; #pragma unroll
;       for (int m = 0; m < 4; ++m) {
;         const int rl = ai * 128 + wr * 64 + m * 16 + fr;
;         const float mean = mr[rl * 2], rs = mr[rl * 2 + 1];
;         const int row = row0 + ai * 128 + m * 16;
; #pragma unroll
;         for (int bj = 0; bj < 2; ++bj)
; #pragma unroll
;           for (int n = 0; n < 2; ++n) {
;             const int col = colb + bj * 128 + n * 16;
;             const f32x4 gg = *(const f32x4*)(g.ln_g + col), bb = *(const f32x4*)(g.ln_b + col);
;             const f32x4 o = (acc[ai][bj][m][n] - mean) * rs * gg + bb;
;             const size_t idx = (size_t)row * 2048 + col;
;             if (g.outf) *(f32x4*)(g.outf + idx) = o;
;             uint2 ob; ob.x = pk2(o[0], o[1]); ob.y = pk2(o[2], o[3]);
;             *(uint2*)(g.outb + idx) = ob;
;           }
;       }
	v_sub_f32_e32 v121, v167, v116
	v_sub_f32_e32 v120, v166, v116
	v_sub_f32_e32 v123, v165, v116
	v_sub_f32_e32 v122, v164, v116
	v_pk_mul_f32 v[122:123], v[116:117], v[122:123] op_sel:[1,0]
	v_pk_mul_f32 v[120:121], v[116:117], v[120:121] op_sel:[1,0]
	v_sub_f32_e32 v105, v105, v116
	v_sub_f32_e32 v104, v104, v116
	v_sub_f32_e32 v101, v101, v116
	v_sub_f32_e32 v100, v100, v116
	v_pk_mul_f32 v[100:101], v[116:117], v[100:101] op_sel:[1,0]
	v_pk_mul_f32 v[104:105], v[116:117], v[104:105] op_sel:[1,0]
	v_sub_f32_e32 v103, v103, v116
	v_sub_f32_e32 v102, v102, v116
	v_pk_mul_f32 v[102:103], v[116:117], v[102:103] op_sel:[1,0]
	v_sub_f32_e32 v89, v89, v118
	v_sub_f32_e32 v88, v88, v118
	v_sub_f32_e32 v85, v85, v118
	v_sub_f32_e32 v84, v84, v118
	v_pk_mul_f32 v[84:85], v[118:119], v[84:85] op_sel:[1,0]
	v_pk_mul_f32 v[88:89], v[118:119], v[88:89] op_sel:[1,0]
	v_sub_f32_e32 v87, v87, v118
	v_sub_f32_e32 v86, v86, v118
	v_pk_mul_f32 v[86:87], v[118:119], v[86:87] op_sel:[1,0]
	v_pk_fma_f32 v[28:29], v[226:227], v[120:121], v[242:243]
	v_pk_fma_f32 v[26:27], v[224:225], v[122:123], v[240:241]
	s_nop 0
	v_cvt_pk_bf16_f32 v26, v26, v27
	v_cvt_pk_bf16_f32 v27, v28, v29
	global_store_dwordx2 v[126:127], v[26:27], off
	s_nop 0
	v_pk_fma_f32 v[28:29], v[104:105], v[230:231], v[246:247]
	v_pk_fma_f32 v[26:27], v[100:101], v[228:229], v[244:245]
	v_sub_f32_e32 v101, v109, v116
	v_cvt_pk_bf16_f32 v26, v26, v27
	v_cvt_pk_bf16_f32 v27, v28, v29
	global_store_dwordx2 v[114:115], v[26:27], off offset:32
	s_nop 0
	v_sub_f32_e32 v100, v108, v116
	v_pk_mul_f32 v[100:101], v[116:117], v[100:101] op_sel:[1,0]
	v_pk_fma_f32 v[26:27], v[102:103], v[232:233], v[248:249]
	v_pk_fma_f32 v[28:29], v[100:101], v[234:235], v[250:251]
	v_cvt_pk_bf16_f32 v26, v26, v27
	v_cvt_pk_bf16_f32 v27, v28, v29
	global_store_dwordx2 v[114:115], v[26:27], off offset:256
	s_nop 0
	v_sub_f32_e32 v101, v113, v116
	v_sub_f32_e32 v100, v112, v116
	v_sub_f32_e32 v103, v107, v116
	v_sub_f32_e32 v102, v106, v116
	v_pk_mul_f32 v[102:103], v[116:117], v[102:103] op_sel:[1,0]
	v_pk_mul_f32 v[100:101], v[116:117], v[100:101] op_sel:[1,0]
	v_pk_fma_f32 v[26:27], v[102:103], v[236:237], v[194:195]
	v_pk_fma_f32 v[28:29], v[100:101], v[238:239], v[196:197]
	v_cvt_pk_bf16_f32 v26, v26, v27
	v_cvt_pk_bf16_f32 v27, v28, v29
	global_store_dwordx2 v[114:115], v[26:27], off offset:288
	s_nop 0
	v_sub_f32_e32 v101, v171, v118
	v_sub_f32_e32 v100, v170, v118
	v_sub_f32_e32 v103, v169, v118
	v_sub_f32_e32 v102, v168, v118
	v_pk_mul_f32 v[102:103], v[118:119], v[102:103] op_sel:[1,0]
	v_pk_mul_f32 v[100:101], v[118:119], v[100:101] op_sel:[1,0]
	v_pk_fma_f32 v[26:27], v[224:225], v[102:103], v[240:241]
	v_pk_fma_f32 v[28:29], v[226:227], v[100:101], v[242:243]
	v_cvt_pk_bf16_f32 v26, v26, v27
	v_cvt_pk_bf16_f32 v27, v28, v29
	global_store_dwordx2 v[110:111], v[26:27], off
	s_nop 0
	v_pk_fma_f32 v[28:29], v[88:89], v[230:231], v[246:247]
	v_pk_fma_f32 v[26:27], v[84:85], v[228:229], v[244:245]
	v_sub_f32_e32 v85, v93, v118
	v_cvt_pk_bf16_f32 v26, v26, v27
	v_cvt_pk_bf16_f32 v27, v28, v29
	global_store_dwordx2 v[98:99], v[26:27], off offset:32
	s_nop 0
	v_sub_f32_e32 v84, v92, v118
	v_pk_mul_f32 v[84:85], v[118:119], v[84:85] op_sel:[1,0]
	v_pk_fma_f32 v[26:27], v[86:87], v[232:233], v[248:249]
	v_pk_fma_f32 v[28:29], v[84:85], v[234:235], v[250:251]
	v_cvt_pk_bf16_f32 v26, v26, v27
	v_cvt_pk_bf16_f32 v27, v28, v29
	global_store_dwordx2 v[98:99], v[26:27], off offset:256
	s_nop 0
	v_sub_f32_e32 v85, v97, v118
	v_sub_f32_e32 v84, v96, v118
	v_sub_f32_e32 v87, v91, v118
	v_sub_f32_e32 v86, v90, v118
	v_pk_mul_f32 v[86:87], v[118:119], v[86:87] op_sel:[1,0]
	v_pk_mul_f32 v[84:85], v[118:119], v[84:85] op_sel:[1,0]
	v_pk_fma_f32 v[26:27], v[86:87], v[236:237], v[194:195]
	v_pk_fma_f32 v[28:29], v[84:85], v[238:239], v[196:197]
	v_cvt_pk_bf16_f32 v26, v26, v27
	v_cvt_pk_bf16_f32 v27, v28, v29
	global_store_dwordx2 v[98:99], v[26:27], off offset:288
	s_nop 0
	ds_read_b64 v[84:85], v25 offset:8192
	s_waitcnt lgkmcnt(0)
	v_sub_f32_e32 v87, v175, v84
	v_sub_f32_e32 v86, v174, v84
	v_sub_f32_e32 v89, v173, v84
	v_sub_f32_e32 v88, v172, v84
	v_pk_mul_f32 v[88:89], v[84:85], v[88:89] op_sel:[1,0]
	v_pk_mul_f32 v[86:87], v[84:85], v[86:87] op_sel:[1,0]
	v_sub_f32_e32 v73, v73, v84
	v_sub_f32_e32 v72, v72, v84
	v_sub_f32_e32 v69, v69, v84
	v_sub_f32_e32 v68, v68, v84
	v_pk_mul_f32 v[68:69], v[84:85], v[68:69] op_sel:[1,0]
	v_pk_mul_f32 v[72:73], v[84:85], v[72:73] op_sel:[1,0]
	v_sub_f32_e32 v71, v71, v84
	v_sub_f32_e32 v70, v70, v84
	v_pk_mul_f32 v[70:71], v[84:85], v[70:71] op_sel:[1,0]
	v_pk_fma_f32 v[28:29], v[226:227], v[86:87], v[242:243]
	v_pk_fma_f32 v[26:27], v[224:225], v[88:89], v[240:241]
	s_nop 0
	v_cvt_pk_bf16_f32 v26, v26, v27
	v_cvt_pk_bf16_f32 v27, v28, v29
	global_store_dwordx2 v[94:95], v[26:27], off
	s_nop 0
	v_pk_fma_f32 v[28:29], v[72:73], v[230:231], v[246:247]
	v_pk_fma_f32 v[26:27], v[68:69], v[228:229], v[244:245]
	v_sub_f32_e32 v69, v77, v84
	v_cvt_pk_bf16_f32 v26, v26, v27
	v_cvt_pk_bf16_f32 v27, v28, v29
	global_store_dwordx2 v[82:83], v[26:27], off offset:32
	s_nop 0
	v_sub_f32_e32 v68, v76, v84
	v_pk_mul_f32 v[68:69], v[84:85], v[68:69] op_sel:[1,0]
	v_pk_fma_f32 v[26:27], v[70:71], v[232:233], v[248:249]
	v_pk_fma_f32 v[28:29], v[68:69], v[234:235], v[250:251]
	v_cvt_pk_bf16_f32 v26, v26, v27
	v_cvt_pk_bf16_f32 v27, v28, v29
	global_store_dwordx2 v[82:83], v[26:27], off offset:256
	s_nop 0
	v_sub_f32_e32 v69, v81, v84
	v_sub_f32_e32 v68, v80, v84
	v_sub_f32_e32 v71, v75, v84
	v_sub_f32_e32 v70, v74, v84
	v_pk_mul_f32 v[70:71], v[84:85], v[70:71] op_sel:[1,0]
	v_pk_mul_f32 v[68:69], v[84:85], v[68:69] op_sel:[1,0]
	v_pk_fma_f32 v[26:27], v[70:71], v[236:237], v[194:195]
	v_pk_fma_f32 v[28:29], v[68:69], v[238:239], v[196:197]
	v_cvt_pk_bf16_f32 v26, v26, v27
	v_cvt_pk_bf16_f32 v27, v28, v29
	global_store_dwordx2 v[82:83], v[26:27], off offset:288
	s_nop 0
	ds_read2_b64 v[68:71], v24 offset0:144 offset1:160
	s_waitcnt lgkmcnt(0)
; template <int EPI>
; DI void gemm_unit(const GemmP& g, int pm, int pn) {
;     ...
; #pragma unroll
;     for (int ai = 0; ai < 2; ++ai)
; #pragma unroll
;       for (int m = 0; m < 4; ++m) {
;         const int rl = ai * 128 + wr * 64 + m * 16 + fr;
;         const float mean = mr[rl * 2], rs = mr[rl * 2 + 1];
;         const int row = row0 + ai * 128 + m * 16;
; #pragma unroll
;         for (int bj = 0; bj < 2; ++bj)
; #pragma unroll
;           for (int n = 0; n < 2; ++n) {
;             const int col = colb + bj * 128 + n * 16;
;             const f32x4 gg = *(const f32x4*)(g.ln_g + col), bb = *(const f32x4*)(g.ln_b + col);
;             const f32x4 o = (acc[ai][bj][m][n] - mean) * rs * gg + bb;
;             const size_t idx = (size_t)row * 2048 + col;
;             if (g.outf) *(f32x4*)(g.outf + idx) = o;
;             uint2 ob; ob.x = pk2(o[0], o[1]); ob.y = pk2(o[2], o[3]);
;             *(uint2*)(g.outb + idx) = ob;
;           }
;       }
	v_sub_f32_e32 v25, v179, v68
	v_sub_f32_e32 v24, v178, v68
	v_sub_f32_e32 v73, v177, v68
	v_sub_f32_e32 v72, v176, v68
	v_pk_mul_f32 v[72:73], v[68:69], v[72:73] op_sel:[1,0]
	v_pk_mul_f32 v[24:25], v[68:69], v[24:25] op_sel:[1,0]
	v_sub_f32_e32 v57, v57, v68
	v_sub_f32_e32 v56, v56, v68
	v_sub_f32_e32 v53, v53, v68
	v_sub_f32_e32 v52, v52, v68
	v_pk_mul_f32 v[52:53], v[68:69], v[52:53] op_sel:[1,0]
	v_pk_mul_f32 v[56:57], v[68:69], v[56:57] op_sel:[1,0]
	v_sub_f32_e32 v55, v55, v68
	v_sub_f32_e32 v54, v54, v68
	v_pk_mul_f32 v[54:55], v[68:69], v[54:55] op_sel:[1,0]
	v_sub_f32_e32 v41, v41, v70
	v_sub_f32_e32 v40, v40, v70
	v_sub_f32_e32 v37, v37, v70
	v_sub_f32_e32 v36, v36, v70
	v_pk_mul_f32 v[36:37], v[70:71], v[36:37] op_sel:[1,0]
	v_pk_mul_f32 v[40:41], v[70:71], v[40:41] op_sel:[1,0]
	v_sub_f32_e32 v39, v39, v70
	v_sub_f32_e32 v38, v38, v70
	v_pk_mul_f32 v[38:39], v[70:71], v[38:39] op_sel:[1,0]
	v_pk_fma_f32 v[24:25], v[226:227], v[24:25], v[242:243]
	v_pk_fma_f32 v[26:27], v[224:225], v[72:73], v[240:241]
	v_lshl_add_u64 v[32:33], v[66:67], 1, s[66:67]
	v_cvt_pk_bf16_f32 v26, v26, v27
	v_cvt_pk_bf16_f32 v27, v24, v25
	global_store_dwordx2 v[78:79], v[26:27], off
	s_nop 0
	v_lshl_add_u64 v[32:33], v[32:33], 0, v[22:23]
	v_pk_fma_f32 v[26:27], v[56:57], v[230:231], v[246:247]
	v_pk_fma_f32 v[24:25], v[52:53], v[228:229], v[244:245]
	v_sub_f32_e32 v53, v61, v68
	v_cvt_pk_bf16_f32 v24, v24, v25
	v_cvt_pk_bf16_f32 v25, v26, v27
	global_store_dwordx2 v[32:33], v[24:25], off offset:32
	s_nop 0
	v_sub_f32_e32 v52, v60, v68
	v_pk_mul_f32 v[52:53], v[68:69], v[52:53] op_sel:[1,0]
	v_pk_fma_f32 v[24:25], v[54:55], v[232:233], v[248:249]
	v_pk_fma_f32 v[26:27], v[52:53], v[234:235], v[250:251]
	v_cvt_pk_bf16_f32 v24, v24, v25
	v_cvt_pk_bf16_f32 v25, v26, v27
	global_store_dwordx2 v[32:33], v[24:25], off offset:256
	s_nop 0
	v_sub_f32_e32 v53, v65, v68
	v_sub_f32_e32 v52, v64, v68
	v_sub_f32_e32 v55, v59, v68
	v_sub_f32_e32 v54, v58, v68
	v_pk_mul_f32 v[54:55], v[68:69], v[54:55] op_sel:[1,0]
	v_pk_mul_f32 v[52:53], v[68:69], v[52:53] op_sel:[1,0]
	v_pk_fma_f32 v[24:25], v[54:55], v[236:237], v[194:195]
	v_pk_fma_f32 v[26:27], v[52:53], v[238:239], v[196:197]
	v_cvt_pk_bf16_f32 v24, v24, v25
	v_cvt_pk_bf16_f32 v25, v26, v27
	global_store_dwordx2 v[32:33], v[24:25], off offset:288
	s_nop 0
	v_sub_f32_e32 v33, v183, v70
	v_sub_f32_e32 v32, v182, v70
	v_sub_f32_e32 v53, v181, v70
	v_sub_f32_e32 v52, v180, v70
	v_pk_mul_f32 v[52:53], v[70:71], v[52:53] op_sel:[1,0]
	v_pk_mul_f32 v[32:33], v[70:71], v[32:33] op_sel:[1,0]
	v_pk_fma_f32 v[24:25], v[224:225], v[52:53], v[240:241]
	v_pk_fma_f32 v[26:27], v[226:227], v[32:33], v[242:243]
	v_cvt_pk_bf16_f32 v24, v24, v25
	v_cvt_pk_bf16_f32 v25, v26, v27
	global_store_dwordx2 v[62:63], v[24:25], off
	s_nop 0
	v_lshl_add_u64 v[32:33], v[50:51], 1, s[66:67]
	v_lshl_add_u64 v[32:33], v[32:33], 0, v[22:23]
	v_pk_fma_f32 v[26:27], v[40:41], v[230:231], v[246:247]
	v_pk_fma_f32 v[24:25], v[36:37], v[228:229], v[244:245]
	v_sub_f32_e32 v37, v45, v70
	v_cvt_pk_bf16_f32 v24, v24, v25
	v_cvt_pk_bf16_f32 v25, v26, v27
	global_store_dwordx2 v[32:33], v[24:25], off offset:32
	s_nop 0
	v_sub_f32_e32 v36, v44, v70
	v_pk_mul_f32 v[36:37], v[70:71], v[36:37] op_sel:[1,0]
	v_pk_fma_f32 v[24:25], v[38:39], v[232:233], v[248:249]
	v_pk_fma_f32 v[26:27], v[36:37], v[234:235], v[250:251]
	v_cvt_pk_bf16_f32 v24, v24, v25
	v_cvt_pk_bf16_f32 v25, v26, v27
	global_store_dwordx2 v[32:33], v[24:25], off offset:256
	s_nop 0
	v_sub_f32_e32 v37, v49, v70
	v_sub_f32_e32 v36, v48, v70
	v_sub_f32_e32 v39, v43, v70
	v_sub_f32_e32 v38, v42, v70
	v_pk_mul_f32 v[38:39], v[70:71], v[38:39] op_sel:[1,0]
	v_pk_mul_f32 v[36:37], v[70:71], v[36:37] op_sel:[1,0]
	v_pk_fma_f32 v[24:25], v[38:39], v[236:237], v[194:195]
	v_pk_fma_f32 v[26:27], v[36:37], v[238:239], v[196:197]
	v_cvt_pk_bf16_f32 v24, v24, v25
	v_cvt_pk_bf16_f32 v25, v26, v27
	global_store_dwordx2 v[32:33], v[24:25], off offset:288
	s_nop 0
	ds_read_b64 v[32:33], v0 offset:9600
	s_waitcnt lgkmcnt(0)
	v_sub_f32_e32 v17, v17, v32
	v_sub_f32_e32 v16, v16, v32
	v_sub_f32_e32 v15, v15, v32
	v_sub_f32_e32 v14, v14, v32
	v_pk_mul_f32 v[14:15], v[32:33], v[14:15] op_sel:[1,0]
	v_pk_mul_f32 v[16:17], v[32:33], v[16:17] op_sel:[1,0]
	v_sub_f32_e32 v13, v13, v32
	v_sub_f32_e32 v12, v12, v32
	v_sub_f32_e32 v11, v11, v32
	v_sub_f32_e32 v10, v10, v32
	v_pk_mul_f32 v[10:11], v[32:33], v[10:11] op_sel:[1,0]
	v_pk_mul_f32 v[12:13], v[32:33], v[12:13] op_sel:[1,0]
	v_sub_f32_e32 v9, v9, v32
	v_sub_f32_e32 v8, v8, v32
	v_sub_f32_e32 v7, v7, v32
	v_sub_f32_e32 v6, v6, v32
	v_pk_mul_f32 v[6:7], v[32:33], v[6:7] op_sel:[1,0]
	v_pk_mul_f32 v[8:9], v[32:33], v[8:9] op_sel:[1,0]
	v_sub_f32_e32 v5, v5, v32
	v_sub_f32_e32 v4, v4, v32
	v_sub_f32_e32 v3, v3, v32
	v_sub_f32_e32 v2, v2, v32
	v_pk_mul_f32 v[2:3], v[32:33], v[2:3] op_sel:[1,0]
	v_pk_mul_f32 v[4:5], v[32:33], v[4:5] op_sel:[1,0]
	v_pk_fma_f32 v[16:17], v[226:227], v[16:17], v[242:243]
	v_pk_fma_f32 v[14:15], v[224:225], v[14:15], v[240:241]
	v_lshl_add_u64 v[28:29], v[34:35], 1, s[66:67]
	v_cvt_pk_bf16_f32 v14, v14, v15
	v_cvt_pk_bf16_f32 v15, v16, v17
	global_store_dwordx2 v[46:47], v[14:15], off
	s_nop 0
	v_lshl_add_u64 v[22:23], v[28:29], 0, v[22:23]
	v_pk_fma_f32 v[12:13], v[12:13], v[230:231], v[246:247]
	v_pk_fma_f32 v[10:11], v[10:11], v[228:229], v[244:245]
	s_nop 0
	v_cvt_pk_bf16_f32 v10, v10, v11
	v_cvt_pk_bf16_f32 v11, v12, v13
	global_store_dwordx2 v[22:23], v[10:11], off offset:32
	s_nop 0
	v_pk_fma_f32 v[8:9], v[8:9], v[234:235], v[250:251]
	v_pk_fma_f32 v[6:7], v[6:7], v[232:233], v[248:249]
	s_nop 0
	v_cvt_pk_bf16_f32 v6, v6, v7
	v_cvt_pk_bf16_f32 v7, v8, v9
	global_store_dwordx2 v[22:23], v[6:7], off offset:256
	s_nop 0
	v_pk_fma_f32 v[4:5], v[4:5], v[238:239], v[196:197]
	v_pk_fma_f32 v[2:3], v[2:3], v[236:237], v[194:195]
	s_nop 0
	v_cvt_pk_bf16_f32 v2, v2, v3
	v_cvt_pk_bf16_f32 v3, v4, v5
	global_store_dwordx2 v[22:23], v[2:3], off offset:288
	s_barrier
	s_cbranch_vccnz .LBB0_462

; #define BID opqs((int)blockIdx.x)
; template <int MODE>
; DI void self_attn_phase(const Params& p, int qcol, int kcol, int j, char* smem) {
;     ...
;   for (int idx = BID; idx < 512; idx += gridDim.x) {
;     const int bh = idx & 15, qi = idx >> 4;
;     const int qb = (qi < 16) ? (31 - qi) : (qi - 16);
;     const int b = bh >> 3, hd = bh & 7;
;     const int q0 = qb * 256, nkt = 4 * (qb + 1);
;     attn_item<MODE>(H + (size_t)b * S_ * HLD + qcol + hd * 128, HLD, H + (size_t)b * S_ * HLD + kcol + hd * 128, HLD,
;                     VT + ((size_t)b * 1024 + hd * 128) * S_, S_, CAT + (size_t)b * S_ * DM + 1024 + hd * 128, DM,
;                     q0, nkt, FC + (size_t)(b * 8 + hd) * S_, BM + (size_t)b * S_ * 256,
;                     (MODE == 1) ? sqrtf(__uint_as_float(((const unsigned*)(p.ws + O_BAR))[KN_WORD0 + j * 8 + hd])) : 0.f, smem);
.LBB0_485:
	s_andn2_b64 vcc, exec, s[6:7]
	s_cbranch_vccnz .LBB0_496
	v_readlane_b32 s6, v254, 0
	s_cmpk_gt_i32 s6, 0x1ff
	s_cbranch_scc1 .LBB0_496
	v_readfirstlane_b32 s7, v201
	s_nop 3
	s_lshr_b32 s7, s7, 8
	s_cmp_eq_u32 s7, 1
	s_cbranch_scc1 .Lpriodsa_done
	s_setprio 1
.Lpriodsa_done:
	s_add_u32 s7, s90, 0x39480000
	s_addc_u32 s8, s91, 0
	s_branch .LBB0_490

; #define BID opqs((int)blockIdx.x)
; template <int MODE>
; DI void self_attn_phase(const Params& p, int qcol, int kcol, int j, char* smem) {
;     ...
;   for (int idx = BID; idx < 512; idx += gridDim.x) {
;     const int bh = idx & 15, qi = idx >> 4;
;     const int qb = (qi < 16) ? (31 - qi) : (qi - 16);
;     const int b = bh >> 3, hd = bh & 7;
;     const int q0 = qb * 256, nkt = 4 * (qb + 1);
;     attn_item<MODE>(H + (size_t)b * S_ * HLD + qcol + hd * 128, HLD, H + (size_t)b * S_ * HLD + kcol + hd * 128, HLD,
;                     VT + ((size_t)b * 1024 + hd * 128) * S_, S_, CAT + (size_t)b * S_ * DM + 1024 + hd * 128, DM,
;                     q0, nkt, FC + (size_t)(b * 8 + hd) * S_, BM + (size_t)b * S_ * 256,
;                     (MODE == 1) ? sqrtf(__uint_as_float(((const unsigned*)(p.ws + O_BAR))[KN_WORD0 + j * 8 + hd])) : 0.f, smem);
;   }
.LBB0_496:
	s_setprio 0
	s_mov_b64 s[6:7], 0
